# v70 + GEMM K-loops: no-op setprio 0/1 pairs removed, last pad nop slot filled with a hoisted SALU op
# baseline (speedup 1.0000x reference)
; #define PG8_STAGE(bufoff, gbase, voff) do { _Pragma("unroll") for (int _i = 0; _i < 2; ++_i) \
;         __builtin_amdgcn_global_load_lds((const unsigned*)((const char*)(gbase) + (voff)[_i]), (PG8_LAS unsigned*)(lds + (bufoff) + ldsw + _i * 8192), 16, 0, 0); } while (0)
; #define PG8_LDA(dst, b, h) do { _Pragma("unroll") for (int m = 0; m < 4; ++m) _Pragma("unroll") for (int k = 0; k < 2; ++k) dst[m][k] = *(const PG8_LAS bf16x8*)(lds + PG8_SA(b, h) + aoff + m * 2048 + k * 1024); } while (0)
; #define PG8_LDB(dst, b, h) do { _Pragma("unroll") for (int n = 0; n < 2; ++n) _Pragma("unroll") for (int k = 0; k < 2; ++k) dst[n][k] = *(const PG8_LAS bf16x8*)(lds + PG8_SB(b, h) + boff + n * 2048 + k * 1024); } while (0)
; #define PG8_MMA(ai, bj, At, Bt) do { __builtin_amdgcn_s_setprio(1); _Pragma("unroll") for (int m = 0; m < 4; ++m) _Pragma("unroll") for (int n = 0; n < 2; ++n) _Pragma("unroll") for (int k = 0; k < 2; ++k) \
;         acc[ai][bj][m][n] = __builtin_amdgcn_mfma_f32_16x16x32_bf16(Bt[n][k], At[m][k], acc[ai][bj][m][n], 0, 0, 0); __builtin_amdgcn_s_setprio(0); } while (0)
; #define PG8_WAIT_V(n) asm volatile("s_waitcnt vmcnt(" #n ")" ::: "memory")
; #define PG8_WAIT_L(n) asm volatile("s_waitcnt lgkmcnt(" #n ")" ::: "memory")
; #define PG8_BAR __builtin_amdgcn_s_barrier()
; #define PG8_SCHED __builtin_amdgcn_sched_barrier(0)
; template <class Epi, class Sched, bool ALIGN_EPI = false, bool SP2 = false>
; __device__ __forceinline__ void gemm_phase(PG8_LAS unsigned char* lds, const Gemm g, const Sched& S, const Epi& E) {
;     ...
;         for (int t = 0; t < nt; t += 2) {
;             const bool last = (t == nt - 2);
;             const char* a1 = cA + (size_t)(t + 1) * kstep;
;             const char* a2 = last ? nA : cA + (size_t)(t + 2) * kstep; const char* b2 = last ? nB : cB + (size_t)(t + 2) * kstep;
;             const char* a3 = a2 + kstep; const char* b3 = b2 + kstep;
;             if (last && has_next) S.a_ready(nxt);
;             if constexpr (SP2) {
;             PG8_LDB(B0, 0, 0); PG8_LDB(B1, 0, 1); PG8_SCHED; PG8_LDA(At, 0, 0); PG8_STAGE(PG8_SA(1, 1), a1 + hstep, voffA);
;             PG8_WAIT_V(8); PG8_WAIT_L(0); PG8_BAR; PG8_MMA(0, 0, At, B0); PG8_MMA(0, 1, At, B1); PG8_BAR; PG8_SCHED;
;             PG8_LDA(At, 0, 1); PG8_STAGE(PG8_SB(0, 0), b2, voffB); PG8_STAGE(PG8_SB(0, 1), b2 + hstep, voffB); PG8_STAGE(PG8_SA(0, 0), a2, voffA);
.LBB0_100:
	s_add_u32 s28, s8, 0xfffc0080
	s_addc_u32 s29, s9, -1
	s_add_i32 s53, 0, 0x10000
	s_cmp_eq_u32 s45, 12
	s_cselect_b32 s31, s3, s29
	s_cselect_b32 s30, s7, s28
	s_cselect_b32 s29, s11, s44
	s_cselect_b32 s28, s21, s23
	s_add_i32 s56, 0, 0x14000
	v_add_u32_e32 v144, s53, v204
	v_add_u32_e32 v160, s56, v204
	ds_read_b128 v[132:135], v144
	ds_read_b128 v[136:139], v144 offset:1024
	ds_read_b128 v[140:143], v144 offset:2048
	ds_read_b128 v[144:147], v144 offset:3072
	ds_read_b128 v[148:151], v160
	ds_read_b128 v[152:155], v160 offset:1024
	ds_read_b128 v[156:159], v160 offset:2048
	ds_read_b128 v[160:163], v160 offset:3072
	v_lshl_add_u64 v[194:195], s[8:9], 0, v[178:179]
	s_add_i32 m0, s42, 0xc000
	ds_read_b128 v[164:167], v205
	ds_read_b128 v[182:185], v205 offset:1024
	ds_read_b128 v[186:189], v205 offset:2048
	ds_read_b128 v[190:193], v205 offset:3072
	ds_read_b128 v[208:211], v205 offset:4096
	ds_read_b128 v[212:215], v205 offset:5120
	ds_read_b128 v[216:219], v205 offset:6144
	ds_read_b128 v[220:223], v205 offset:7168
	global_load_lds_dwordx4 v[194:195], off
	s_add_i32 m0, s42, 0xe000
	v_lshl_add_u64 v[194:195], s[8:9], 0, v[180:181]
	global_load_lds_dwordx4 v[194:195], off
	s_waitcnt vmcnt(8) lgkmcnt(0)
	s_barrier
	s_setprio 1
	v_mfma_f32_16x16x32_bf16 v[128:131], v[132:135], v[164:167], v[128:131]
	v_mfma_f32_16x16x32_bf16 v[124:127], v[140:143], v[164:167], v[124:127]
	v_mfma_f32_16x16x32_bf16 v[112:115], v[132:135], v[186:189], v[112:115]
	v_mfma_f32_16x16x32_bf16 v[108:111], v[140:143], v[186:189], v[108:111]
	v_mfma_f32_16x16x32_bf16 v[96:99], v[132:135], v[208:211], v[96:99]
	v_mfma_f32_16x16x32_bf16 v[92:95], v[140:143], v[208:211], v[92:95]
	v_mfma_f32_16x16x32_bf16 v[80:83], v[132:135], v[216:219], v[80:83]
	v_mfma_f32_16x16x32_bf16 v[76:79], v[140:143], v[216:219], v[76:79]
	v_mfma_f32_16x16x32_bf16 v[128:131], v[136:139], v[182:185], v[128:131]
	v_mfma_f32_16x16x32_bf16 v[124:127], v[144:147], v[182:185], v[124:127]
	v_mfma_f32_16x16x32_bf16 v[112:115], v[136:139], v[190:193], v[112:115]
	v_mfma_f32_16x16x32_bf16 v[108:111], v[144:147], v[190:193], v[108:111]
	v_mfma_f32_16x16x32_bf16 v[96:99], v[136:139], v[212:215], v[96:99]
	v_mfma_f32_16x16x32_bf16 v[92:95], v[144:147], v[212:215], v[92:95]
	v_mfma_f32_16x16x32_bf16 v[80:83], v[136:139], v[220:223], v[80:83]
	v_mfma_f32_16x16x32_bf16 v[76:79], v[144:147], v[220:223], v[76:79]
	v_mfma_f32_16x16x32_bf16 v[120:123], v[148:151], v[164:167], v[120:123]
	v_mfma_f32_16x16x32_bf16 v[116:119], v[156:159], v[164:167], v[116:119]
	v_mfma_f32_16x16x32_bf16 v[104:107], v[148:151], v[186:189], v[104:107]
	v_mfma_f32_16x16x32_bf16 v[100:103], v[156:159], v[186:189], v[100:103]
	v_mfma_f32_16x16x32_bf16 v[88:91], v[148:151], v[208:211], v[88:91]
	v_mfma_f32_16x16x32_bf16 v[84:87], v[156:159], v[208:211], v[84:87]
	v_mfma_f32_16x16x32_bf16 v[72:75], v[148:151], v[216:219], v[72:75]
	v_mfma_f32_16x16x32_bf16 v[68:71], v[156:159], v[216:219], v[68:71]
	v_mfma_f32_16x16x32_bf16 v[120:123], v[152:155], v[182:185], v[120:123]
	v_mfma_f32_16x16x32_bf16 v[116:119], v[160:163], v[182:185], v[116:119]
	v_mfma_f32_16x16x32_bf16 v[104:107], v[152:155], v[190:193], v[104:107]
	v_mfma_f32_16x16x32_bf16 v[100:103], v[160:163], v[190:193], v[100:103]
	v_mfma_f32_16x16x32_bf16 v[88:91], v[152:155], v[212:215], v[88:91]
	v_mfma_f32_16x16x32_bf16 v[84:87], v[160:163], v[212:215], v[84:87]
	v_mfma_f32_16x16x32_bf16 v[72:75], v[152:155], v[220:223], v[72:75]
	v_mfma_f32_16x16x32_bf16 v[68:71], v[160:163], v[220:223], v[68:71]
	s_setprio 0
	s_barrier
	s_add_i32 s53, s53, s41
	v_lshl_add_u64 v[194:195], s[28:29], 0, v[168:169]
	s_mov_b32 m0, s53
	ds_read_b128 v[164:167], v205 offset:16384
	ds_read_b128 v[182:185], v205 offset:17408
	ds_read_b128 v[186:189], v205 offset:18432
	ds_read_b128 v[190:193], v205 offset:19456
	ds_read_b128 v[208:211], v205 offset:20480
	ds_read_b128 v[212:215], v205 offset:21504
	ds_read_b128 v[216:219], v205 offset:22528
	ds_read_b128 v[220:223], v205 offset:23552
	global_load_lds_dwordx4 v[194:195], off
	s_add_i32 m0, s53, 0x2000
	s_add_u32 s54, s28, 0x40000
	v_lshl_add_u64 v[202:203], s[28:29], 0, v[172:173]
	s_addc_u32 s55, s29, 0
	s_add_i32 s53, s56, s41
	global_load_lds_dwordx4 v[202:203], off
	v_lshl_add_u64 v[224:225], s[54:55], 0, v[168:169]
	s_mov_b32 m0, s53
	v_lshl_add_u64 v[226:227], s[30:31], 0, v[170:171]
	global_load_lds_dwordx4 v[224:225], off
	s_add_i32 m0, s53, 0x2000
	v_lshl_add_u64 v[224:225], s[54:55], 0, v[172:173]
	global_load_lds_dwordx4 v[224:225], off
	s_mov_b32 m0, s42
	v_lshl_add_u64 v[224:225], s[30:31], 0, v[0:1]
	global_load_lds_dwordx4 v[224:225], off
	s_mov_b32 m0, s43
	s_add_i32 s53, 0, 0x18000
	global_load_lds_dwordx4 v[226:227], off
	s_waitcnt vmcnt(8) lgkmcnt(0)
	s_barrier
; #define PG8_STAGE(bufoff, gbase, voff) do { _Pragma("unroll") for (int _i = 0; _i < 2; ++_i) \
;         __builtin_amdgcn_global_load_lds((const unsigned*)((const char*)(gbase) + (voff)[_i]), (PG8_LAS unsigned*)(lds + (bufoff) + ldsw + _i * 8192), 16, 0, 0); } while (0)
; #define PG8_LDA(dst, b, h) do { _Pragma("unroll") for (int m = 0; m < 4; ++m) _Pragma("unroll") for (int k = 0; k < 2; ++k) dst[m][k] = *(const PG8_LAS bf16x8*)(lds + PG8_SA(b, h) + aoff + m * 2048 + k * 1024); } while (0)
; #define PG8_LDB(dst, b, h) do { _Pragma("unroll") for (int n = 0; n < 2; ++n) _Pragma("unroll") for (int k = 0; k < 2; ++k) dst[n][k] = *(const PG8_LAS bf16x8*)(lds + PG8_SB(b, h) + boff + n * 2048 + k * 1024); } while (0)
; #define PG8_MMA(ai, bj, At, Bt) do { __builtin_amdgcn_s_setprio(1); _Pragma("unroll") for (int m = 0; m < 4; ++m) _Pragma("unroll") for (int n = 0; n < 2; ++n) _Pragma("unroll") for (int k = 0; k < 2; ++k) \
;         acc[ai][bj][m][n] = __builtin_amdgcn_mfma_f32_16x16x32_bf16(Bt[n][k], At[m][k], acc[ai][bj][m][n], 0, 0, 0); __builtin_amdgcn_s_setprio(0); } while (0)
; #define PG8_WAIT_V(n) asm volatile("s_waitcnt vmcnt(" #n ")" ::: "memory")
; #define PG8_WAIT_L(n) asm volatile("s_waitcnt lgkmcnt(" #n ")" ::: "memory")
; #define PG8_BAR __builtin_amdgcn_s_barrier()
; #define PG8_SCHED __builtin_amdgcn_sched_barrier(0)
; template <class Epi, class Sched, bool ALIGN_EPI = false, bool SP2 = false>
; __device__ __forceinline__ void gemm_phase(PG8_LAS unsigned char* lds, const Gemm g, const Sched& S, const Epi& E) {
;     ...
;             PG8_WAIT_V(8); PG8_WAIT_L(0); PG8_BAR; PG8_MMA(1, 0, At, B0); PG8_MMA(1, 1, At, B1); PG8_BAR; PG8_SCHED;
;             PG8_LDB(B0, 1, 0); PG8_LDB(B1, 1, 1); PG8_SCHED; PG8_LDA(At, 1, 0); PG8_STAGE(PG8_SA(0, 1), a2 + hstep, voffA);
;             PG8_WAIT_V(8); PG8_WAIT_L(0); PG8_BAR; PG8_MMA(0, 0, At, B0); PG8_MMA(0, 1, At, B1); PG8_BAR; PG8_SCHED;
	s_setprio 1
	v_mfma_f32_16x16x32_bf16 v[64:67], v[132:135], v[164:167], v[64:67]
	v_mfma_f32_16x16x32_bf16 v[60:63], v[140:143], v[164:167], v[60:63]
	v_mfma_f32_16x16x32_bf16 v[48:51], v[132:135], v[186:189], v[48:51]
	v_mfma_f32_16x16x32_bf16 v[44:47], v[140:143], v[186:189], v[44:47]
	v_mfma_f32_16x16x32_bf16 v[32:35], v[132:135], v[208:211], v[32:35]
	v_mfma_f32_16x16x32_bf16 v[28:31], v[140:143], v[208:211], v[28:31]
	v_mfma_f32_16x16x32_bf16 v[16:19], v[132:135], v[216:219], v[16:19]
	v_mfma_f32_16x16x32_bf16 v[12:15], v[140:143], v[216:219], v[12:15]
	v_mfma_f32_16x16x32_bf16 v[64:67], v[136:139], v[182:185], v[64:67]
	v_mfma_f32_16x16x32_bf16 v[60:63], v[144:147], v[182:185], v[60:63]
	v_mfma_f32_16x16x32_bf16 v[48:51], v[136:139], v[190:193], v[48:51]
	v_mfma_f32_16x16x32_bf16 v[44:47], v[144:147], v[190:193], v[44:47]
	v_mfma_f32_16x16x32_bf16 v[32:35], v[136:139], v[212:215], v[32:35]
	v_mfma_f32_16x16x32_bf16 v[28:31], v[144:147], v[212:215], v[28:31]
	v_mfma_f32_16x16x32_bf16 v[16:19], v[136:139], v[220:223], v[16:19]
	v_mfma_f32_16x16x32_bf16 v[12:15], v[144:147], v[220:223], v[12:15]
	v_mfma_f32_16x16x32_bf16 v[56:59], v[148:151], v[164:167], v[56:59]
	v_mfma_f32_16x16x32_bf16 v[52:55], v[156:159], v[164:167], v[52:55]
	v_mfma_f32_16x16x32_bf16 v[40:43], v[148:151], v[186:189], v[40:43]
	v_mfma_f32_16x16x32_bf16 v[36:39], v[156:159], v[186:189], v[36:39]
	v_mfma_f32_16x16x32_bf16 v[24:27], v[148:151], v[208:211], v[24:27]
	v_mfma_f32_16x16x32_bf16 v[20:23], v[156:159], v[208:211], v[20:23]
	v_mfma_f32_16x16x32_bf16 v[8:11], v[148:151], v[216:219], v[8:11]
	v_mfma_f32_16x16x32_bf16 v[4:7], v[156:159], v[216:219], v[4:7]
	v_mfma_f32_16x16x32_bf16 v[56:59], v[152:155], v[182:185], v[56:59]
	v_mfma_f32_16x16x32_bf16 v[52:55], v[160:163], v[182:185], v[52:55]
	v_mfma_f32_16x16x32_bf16 v[40:43], v[152:155], v[190:193], v[40:43]
	v_mfma_f32_16x16x32_bf16 v[36:39], v[160:163], v[190:193], v[36:39]
	v_mfma_f32_16x16x32_bf16 v[24:27], v[152:155], v[212:215], v[24:27]
	v_mfma_f32_16x16x32_bf16 v[20:23], v[160:163], v[212:215], v[20:23]
	v_mfma_f32_16x16x32_bf16 v[8:11], v[152:155], v[220:223], v[8:11]
	v_mfma_f32_16x16x32_bf16 v[4:7], v[160:163], v[220:223], v[4:7]
	s_setprio 0
	s_barrier
	s_add_i32 s54, 0, 0x1c000
	v_add_u32_e32 v144, s53, v204
	v_add_u32_e32 v160, s54, v204
	ds_read_b128 v[132:135], v144
	ds_read_b128 v[136:139], v144 offset:1024
	ds_read_b128 v[140:143], v144 offset:2048
	ds_read_b128 v[144:147], v144 offset:3072
	ds_read_b128 v[148:151], v160
	ds_read_b128 v[152:155], v160 offset:1024
	ds_read_b128 v[156:159], v160 offset:2048
	ds_read_b128 v[160:163], v160 offset:3072
	s_add_u32 s30, s30, 0x40000
	s_addc_u32 s31, s31, 0
	s_mov_b32 m0, s46
	v_lshl_add_u64 v[228:229], s[30:31], 0, v[0:1]
	ds_read_b128 v[164:167], v205 offset:32768
	ds_read_b128 v[182:185], v205 offset:33792
	ds_read_b128 v[186:189], v205 offset:34816
	ds_read_b128 v[190:193], v205 offset:35840
	ds_read_b128 v[208:211], v205 offset:36864
	ds_read_b128 v[212:215], v205 offset:37888
	ds_read_b128 v[216:219], v205 offset:38912
	ds_read_b128 v[220:223], v205 offset:39936
	global_load_lds_dwordx4 v[228:229], off
	s_mov_b32 m0, s47
	v_lshl_add_u64 v[228:229], s[30:31], 0, v[170:171]
	global_load_lds_dwordx4 v[228:229], off
	s_waitcnt vmcnt(8) lgkmcnt(0)
	s_barrier
	s_setprio 1
	v_mfma_f32_16x16x32_bf16 v[128:131], v[132:135], v[164:167], v[128:131]
	v_mfma_f32_16x16x32_bf16 v[124:127], v[140:143], v[164:167], v[124:127]
	v_mfma_f32_16x16x32_bf16 v[112:115], v[132:135], v[186:189], v[112:115]
	v_mfma_f32_16x16x32_bf16 v[108:111], v[140:143], v[186:189], v[108:111]
	v_mfma_f32_16x16x32_bf16 v[96:99], v[132:135], v[208:211], v[96:99]
	v_mfma_f32_16x16x32_bf16 v[92:95], v[140:143], v[208:211], v[92:95]
	v_mfma_f32_16x16x32_bf16 v[80:83], v[132:135], v[216:219], v[80:83]
	v_mfma_f32_16x16x32_bf16 v[76:79], v[140:143], v[216:219], v[76:79]
	v_mfma_f32_16x16x32_bf16 v[128:131], v[136:139], v[182:185], v[128:131]
	v_mfma_f32_16x16x32_bf16 v[124:127], v[144:147], v[182:185], v[124:127]
	v_mfma_f32_16x16x32_bf16 v[112:115], v[136:139], v[190:193], v[112:115]
	v_mfma_f32_16x16x32_bf16 v[108:111], v[144:147], v[190:193], v[108:111]
	v_mfma_f32_16x16x32_bf16 v[96:99], v[136:139], v[212:215], v[96:99]
	v_mfma_f32_16x16x32_bf16 v[92:95], v[144:147], v[212:215], v[92:95]
	v_mfma_f32_16x16x32_bf16 v[80:83], v[136:139], v[220:223], v[80:83]
	v_mfma_f32_16x16x32_bf16 v[76:79], v[144:147], v[220:223], v[76:79]
	v_mfma_f32_16x16x32_bf16 v[120:123], v[148:151], v[164:167], v[120:123]
	v_mfma_f32_16x16x32_bf16 v[116:119], v[156:159], v[164:167], v[116:119]
	v_mfma_f32_16x16x32_bf16 v[104:107], v[148:151], v[186:189], v[104:107]
	v_mfma_f32_16x16x32_bf16 v[100:103], v[156:159], v[186:189], v[100:103]
	v_mfma_f32_16x16x32_bf16 v[88:91], v[148:151], v[208:211], v[88:91]
	v_mfma_f32_16x16x32_bf16 v[84:87], v[156:159], v[208:211], v[84:87]
	v_mfma_f32_16x16x32_bf16 v[72:75], v[148:151], v[216:219], v[72:75]
	v_mfma_f32_16x16x32_bf16 v[68:71], v[156:159], v[216:219], v[68:71]
	v_mfma_f32_16x16x32_bf16 v[120:123], v[152:155], v[182:185], v[120:123]
	v_mfma_f32_16x16x32_bf16 v[116:119], v[160:163], v[182:185], v[116:119]
	v_mfma_f32_16x16x32_bf16 v[104:107], v[152:155], v[190:193], v[104:107]
	v_mfma_f32_16x16x32_bf16 v[100:103], v[160:163], v[190:193], v[100:103]
	v_mfma_f32_16x16x32_bf16 v[88:91], v[152:155], v[212:215], v[88:91]
	v_mfma_f32_16x16x32_bf16 v[84:87], v[160:163], v[212:215], v[84:87]
	v_mfma_f32_16x16x32_bf16 v[72:75], v[152:155], v[220:223], v[72:75]
	v_mfma_f32_16x16x32_bf16 v[68:71], v[160:163], v[220:223], v[68:71]
	s_setprio 0
	s_barrier
; #define PG8_STAGE(bufoff, gbase, voff) do { _Pragma("unroll") for (int _i = 0; _i < 2; ++_i) \
;         __builtin_amdgcn_global_load_lds((const unsigned*)((const char*)(gbase) + (voff)[_i]), (PG8_LAS unsigned*)(lds + (bufoff) + ldsw + _i * 8192), 16, 0, 0); } while (0)
; #define PG8_LDA(dst, b, h) do { _Pragma("unroll") for (int m = 0; m < 4; ++m) _Pragma("unroll") for (int k = 0; k < 2; ++k) dst[m][k] = *(const PG8_LAS bf16x8*)(lds + PG8_SA(b, h) + aoff + m * 2048 + k * 1024); } while (0)
; #define PG8_MMA(ai, bj, At, Bt) do { __builtin_amdgcn_s_setprio(1); _Pragma("unroll") for (int m = 0; m < 4; ++m) _Pragma("unroll") for (int n = 0; n < 2; ++n) _Pragma("unroll") for (int k = 0; k < 2; ++k) \
;         acc[ai][bj][m][n] = __builtin_amdgcn_mfma_f32_16x16x32_bf16(Bt[n][k], At[m][k], acc[ai][bj][m][n], 0, 0, 0); __builtin_amdgcn_s_setprio(0); } while (0)
; #define PG8_WAIT_V(n) asm volatile("s_waitcnt vmcnt(" #n ")" ::: "memory")
; #define PG8_WAIT_L(n) asm volatile("s_waitcnt lgkmcnt(" #n ")" ::: "memory")
; #define PG8_BAR __builtin_amdgcn_s_barrier()
; #define PG8_SCHED __builtin_amdgcn_sched_barrier(0)
; template <class Epi, class Sched, bool ALIGN_EPI = false, bool SP2 = false>
; __device__ __forceinline__ void gemm_phase(PG8_LAS unsigned char* lds, const Gemm g, const Sched& S, const Epi& E) {
;     ...
;         for (int t = 0; t < nt; t += 2) {
;             const bool last = (t == nt - 2);
;             const char* a1 = cA + (size_t)(t + 1) * kstep;
;             const char* a2 = last ? nA : cA + (size_t)(t + 2) * kstep; const char* b2 = last ? nB : cB + (size_t)(t + 2) * kstep;
;     ...
;             PG8_LDA(At, 1, 1); PG8_STAGE(PG8_SB(1, 0), b3, voffB); PG8_STAGE(PG8_SB(1, 1), b3 + hstep, voffB); PG8_STAGE(PG8_SA(1, 0), a3, voffA);
;             PG8_WAIT_V(8); PG8_WAIT_L(0); PG8_BAR; PG8_MMA(1, 0, At, B0); PG8_MMA(1, 1, At, B1); PG8_BAR; PG8_SCHED;
	s_add_i32 s30, s53, s41
	v_lshl_add_u64 v[194:195], v[194:195], 0, s[82:83]
	s_mov_b32 m0, s30
	ds_read_b128 v[164:167], v205 offset:49152
	ds_read_b128 v[182:185], v205 offset:50176
	ds_read_b128 v[186:189], v205 offset:51200
	ds_read_b128 v[190:193], v205 offset:52224
	ds_read_b128 v[208:211], v205 offset:53248
	ds_read_b128 v[212:215], v205 offset:54272
	ds_read_b128 v[216:219], v205 offset:55296
	ds_read_b128 v[220:223], v205 offset:56320
	global_load_lds_dwordx4 v[194:195], off
	s_add_i32 m0, s30, 0x2000
	s_add_u32 s28, s28, 0x40080
	v_lshl_add_u64 v[194:195], v[202:203], 0, s[82:83]
	s_addc_u32 s29, s29, 0
	s_add_i32 s30, s54, s41
	global_load_lds_dwordx4 v[194:195], off
	s_mov_b32 m0, s30
	v_lshl_add_u64 v[194:195], s[28:29], 0, v[168:169]
	global_load_lds_dwordx4 v[194:195], off
	s_add_i32 m0, s30, 0x2000
	v_lshl_add_u64 v[194:195], s[28:29], 0, v[172:173]
	global_load_lds_dwordx4 v[194:195], off
	s_mov_b32 m0, s50
	v_lshl_add_u64 v[194:195], v[224:225], 0, s[82:83]
	global_load_lds_dwordx4 v[194:195], off
	s_mov_b32 m0, s51
	v_lshl_add_u64 v[194:195], v[226:227], 0, s[82:83]
	global_load_lds_dwordx4 v[194:195], off
	s_waitcnt vmcnt(8) lgkmcnt(0)
	s_barrier
	s_setprio 1
	v_mfma_f32_16x16x32_bf16 v[64:67], v[132:135], v[164:167], v[64:67]
	v_mfma_f32_16x16x32_bf16 v[60:63], v[140:143], v[164:167], v[60:63]
	v_mfma_f32_16x16x32_bf16 v[48:51], v[132:135], v[186:189], v[48:51]
	v_mfma_f32_16x16x32_bf16 v[44:47], v[140:143], v[186:189], v[44:47]
	v_mfma_f32_16x16x32_bf16 v[32:35], v[132:135], v[208:211], v[32:35]
	v_mfma_f32_16x16x32_bf16 v[28:31], v[140:143], v[208:211], v[28:31]
	v_mfma_f32_16x16x32_bf16 v[16:19], v[132:135], v[216:219], v[16:19]
	v_mfma_f32_16x16x32_bf16 v[12:15], v[140:143], v[216:219], v[12:15]
	v_mfma_f32_16x16x32_bf16 v[64:67], v[136:139], v[182:185], v[64:67]
	v_mfma_f32_16x16x32_bf16 v[60:63], v[144:147], v[182:185], v[60:63]
	v_mfma_f32_16x16x32_bf16 v[48:51], v[136:139], v[190:193], v[48:51]
	v_mfma_f32_16x16x32_bf16 v[44:47], v[144:147], v[190:193], v[44:47]
	v_mfma_f32_16x16x32_bf16 v[32:35], v[136:139], v[212:215], v[32:35]
	v_mfma_f32_16x16x32_bf16 v[28:31], v[144:147], v[212:215], v[28:31]
	v_mfma_f32_16x16x32_bf16 v[16:19], v[136:139], v[220:223], v[16:19]
	v_mfma_f32_16x16x32_bf16 v[12:15], v[144:147], v[220:223], v[12:15]
	v_mfma_f32_16x16x32_bf16 v[56:59], v[148:151], v[164:167], v[56:59]
	v_mfma_f32_16x16x32_bf16 v[52:55], v[156:159], v[164:167], v[52:55]
	v_mfma_f32_16x16x32_bf16 v[40:43], v[148:151], v[186:189], v[40:43]
	v_mfma_f32_16x16x32_bf16 v[36:39], v[156:159], v[186:189], v[36:39]
	v_mfma_f32_16x16x32_bf16 v[24:27], v[148:151], v[208:211], v[24:27]
	v_mfma_f32_16x16x32_bf16 v[20:23], v[156:159], v[208:211], v[20:23]
	v_mfma_f32_16x16x32_bf16 v[8:11], v[148:151], v[216:219], v[8:11]
	v_mfma_f32_16x16x32_bf16 v[4:7], v[156:159], v[216:219], v[4:7]
	v_mfma_f32_16x16x32_bf16 v[56:59], v[152:155], v[182:185], v[56:59]
	v_mfma_f32_16x16x32_bf16 v[52:55], v[160:163], v[182:185], v[52:55]
	v_mfma_f32_16x16x32_bf16 v[40:43], v[152:155], v[190:193], v[40:43]
	v_mfma_f32_16x16x32_bf16 v[36:39], v[160:163], v[190:193], v[36:39]
	v_mfma_f32_16x16x32_bf16 v[24:27], v[152:155], v[212:215], v[24:27]
	v_mfma_f32_16x16x32_bf16 v[20:23], v[160:163], v[212:215], v[20:23]
	v_mfma_f32_16x16x32_bf16 v[8:11], v[152:155], v[220:223], v[8:11]
	v_mfma_f32_16x16x32_bf16 v[4:7], v[160:163], v[220:223], v[4:7]
	s_setprio 0
	s_barrier
	s_add_i32 s45, s45, 2
	s_add_u32 s8, s8, 0x100
	s_addc_u32 s9, s9, 0
	s_add_u32 s23, s23, 0x100
	s_addc_u32 s44, s44, 0
	s_cmp_gt_u32 s45, 13
	s_cbranch_scc0 .LBB0_100
	s_and_b64 vcc, exec, s[14:15]
	s_cbranch_vccz .LBB0_103
	s_barrier

; #define PG8_STAGE(bufoff, gbase, voff) do { _Pragma("unroll") for (int _i = 0; _i < 2; ++_i) \
;         __builtin_amdgcn_global_load_lds((const unsigned*)((const char*)(gbase) + (voff)[_i]), (PG8_LAS unsigned*)(lds + (bufoff) + ldsw + _i * 8192), 16, 0, 0); } while (0)
; #define PG8_LDA(dst, b, h) do { _Pragma("unroll") for (int m = 0; m < 4; ++m) _Pragma("unroll") for (int k = 0; k < 2; ++k) dst[m][k] = *(const PG8_LAS bf16x8*)(lds + PG8_SA(b, h) + aoff + m * 2048 + k * 1024); } while (0)
; #define PG8_LDB(dst, b, h) do { _Pragma("unroll") for (int n = 0; n < 2; ++n) _Pragma("unroll") for (int k = 0; k < 2; ++k) dst[n][k] = *(const PG8_LAS bf16x8*)(lds + PG8_SB(b, h) + boff + n * 2048 + k * 1024); } while (0)
; #define PG8_MMA(ai, bj, At, Bt) do { __builtin_amdgcn_s_setprio(1); _Pragma("unroll") for (int m = 0; m < 4; ++m) _Pragma("unroll") for (int n = 0; n < 2; ++n) _Pragma("unroll") for (int k = 0; k < 2; ++k) \
;         acc[ai][bj][m][n] = __builtin_amdgcn_mfma_f32_16x16x32_bf16(Bt[n][k], At[m][k], acc[ai][bj][m][n], 0, 0, 0); __builtin_amdgcn_s_setprio(0); } while (0)
; #define PG8_WAIT_V(n) asm volatile("s_waitcnt vmcnt(" #n ")" ::: "memory")
; #define PG8_WAIT_L(n) asm volatile("s_waitcnt lgkmcnt(" #n ")" ::: "memory")
; #define PG8_BAR __builtin_amdgcn_s_barrier()
; #define PG8_SCHED __builtin_amdgcn_sched_barrier(0)
; template <class Epi, class Sched, bool ALIGN_EPI = false, bool SP2 = false>
; __device__ __forceinline__ void gemm_phase(PG8_LAS unsigned char* lds, const Gemm g, const Sched& S, const Epi& E) {
;     ...
;         for (int t = 0; t < nt; t += 2) {
;             const bool last = (t == nt - 2);
;             const char* a1 = cA + (size_t)(t + 1) * kstep;
;             const char* a2 = last ? nA : cA + (size_t)(t + 2) * kstep; const char* b2 = last ? nB : cB + (size_t)(t + 2) * kstep;
;             const char* a3 = a2 + kstep; const char* b3 = b2 + kstep;
;             if (last && has_next) S.a_ready(nxt);
;             if constexpr (SP2) {
;             PG8_LDB(B0, 0, 0); PG8_LDB(B1, 0, 1); PG8_SCHED; PG8_LDA(At, 0, 0); PG8_STAGE(PG8_SA(1, 1), a1 + hstep, voffA);
;             PG8_WAIT_V(8); PG8_WAIT_L(0); PG8_BAR; PG8_MMA(0, 0, At, B0); PG8_MMA(0, 1, At, B1); PG8_BAR; PG8_SCHED;
;             PG8_LDA(At, 0, 1); PG8_STAGE(PG8_SB(0, 0), b2, voffB); PG8_STAGE(PG8_SB(0, 1), b2 + hstep, voffB); PG8_STAGE(PG8_SA(0, 0), a2, voffA);
.LBB0_329:
	s_add_u32 s30, s28, 0xfffc0080
	s_addc_u32 s31, s29, -1
	s_add_i32 s52, 0, 0x10000
	s_cmp_eq_u32 s45, 12
	s_cselect_b32 s35, s3, s31
	s_cselect_b32 s34, s17, s30
	s_cselect_b32 s31, s19, s44
	s_cselect_b32 s30, s25, s27
	s_add_i32 s54, 0, 0x14000
	v_add_u32_e32 v128, s52, v251
	v_add_u32_e32 v156, s54, v251
	ds_read_b128 v[108:111], v128
	ds_read_b128 v[112:115], v128 offset:1024
	ds_read_b128 v[124:127], v128 offset:2048
	ds_read_b128 v[128:131], v128 offset:3072
	ds_read_b128 v[132:135], v156
	ds_read_b128 v[140:143], v156 offset:1024
	ds_read_b128 v[148:151], v156 offset:2048
	ds_read_b128 v[156:159], v156 offset:3072
	v_lshl_add_u64 v[212:213], s[28:29], 0, v[208:209]
	s_add_i32 m0, s42, 0xc000
	ds_read_b128 v[164:167], v253
	ds_read_b128 v[168:171], v253 offset:1024
	ds_read_b128 v[172:175], v253 offset:2048
	ds_read_b128 v[176:179], v253 offset:3072
	ds_read_b128 v[180:183], v253 offset:4096
	ds_read_b128 v[184:187], v253 offset:5120
	ds_read_b128 v[188:191], v253 offset:6144
	ds_read_b128 v[192:195], v253 offset:7168
	global_load_lds_dwordx4 v[212:213], off
	s_add_i32 m0, s42, 0xe000
	v_lshl_add_u64 v[212:213], s[28:29], 0, v[210:211]
	global_load_lds_dwordx4 v[212:213], off
	s_waitcnt vmcnt(8) lgkmcnt(0)
	s_barrier
	s_setprio 1
	v_mfma_f32_16x16x32_bf16 v[160:163], v[108:111], v[164:167], v[160:163]
	v_mfma_f32_16x16x32_bf16 v[152:155], v[124:127], v[164:167], v[152:155]
	v_mfma_f32_16x16x32_bf16 v[120:123], v[108:111], v[172:175], v[120:123]
	v_mfma_f32_16x16x32_bf16 v[116:119], v[124:127], v[172:175], v[116:119]
	v_mfma_f32_16x16x32_bf16 v[96:99], v[108:111], v[180:183], v[96:99]
	v_mfma_f32_16x16x32_bf16 v[92:95], v[124:127], v[180:183], v[92:95]
	v_mfma_f32_16x16x32_bf16 v[80:83], v[108:111], v[188:191], v[80:83]
	v_mfma_f32_16x16x32_bf16 v[76:79], v[124:127], v[188:191], v[76:79]
	v_mfma_f32_16x16x32_bf16 v[160:163], v[112:115], v[168:171], v[160:163]
	v_mfma_f32_16x16x32_bf16 v[152:155], v[128:131], v[168:171], v[152:155]
	v_mfma_f32_16x16x32_bf16 v[120:123], v[112:115], v[176:179], v[120:123]
	v_mfma_f32_16x16x32_bf16 v[116:119], v[128:131], v[176:179], v[116:119]
	v_mfma_f32_16x16x32_bf16 v[96:99], v[112:115], v[184:187], v[96:99]
	v_mfma_f32_16x16x32_bf16 v[92:95], v[128:131], v[184:187], v[92:95]
	v_mfma_f32_16x16x32_bf16 v[80:83], v[112:115], v[192:195], v[80:83]
	v_mfma_f32_16x16x32_bf16 v[76:79], v[128:131], v[192:195], v[76:79]
	v_mfma_f32_16x16x32_bf16 v[144:147], v[132:135], v[164:167], v[144:147]
	v_mfma_f32_16x16x32_bf16 v[136:139], v[148:151], v[164:167], v[136:139]
	v_mfma_f32_16x16x32_bf16 v[104:107], v[132:135], v[172:175], v[104:107]
	v_mfma_f32_16x16x32_bf16 v[100:103], v[148:151], v[172:175], v[100:103]
	v_mfma_f32_16x16x32_bf16 v[88:91], v[132:135], v[180:183], v[88:91]
	v_mfma_f32_16x16x32_bf16 v[84:87], v[148:151], v[180:183], v[84:87]
	v_mfma_f32_16x16x32_bf16 v[72:75], v[132:135], v[188:191], v[72:75]
	v_mfma_f32_16x16x32_bf16 v[68:71], v[148:151], v[188:191], v[68:71]
	v_mfma_f32_16x16x32_bf16 v[144:147], v[140:143], v[168:171], v[144:147]
	v_mfma_f32_16x16x32_bf16 v[136:139], v[156:159], v[168:171], v[136:139]
	v_mfma_f32_16x16x32_bf16 v[104:107], v[140:143], v[176:179], v[104:107]
	v_mfma_f32_16x16x32_bf16 v[100:103], v[156:159], v[176:179], v[100:103]
	v_mfma_f32_16x16x32_bf16 v[88:91], v[140:143], v[184:187], v[88:91]
	v_mfma_f32_16x16x32_bf16 v[84:87], v[156:159], v[184:187], v[84:87]
	v_mfma_f32_16x16x32_bf16 v[72:75], v[140:143], v[192:195], v[72:75]
	v_mfma_f32_16x16x32_bf16 v[68:71], v[156:159], v[192:195], v[68:71]
	s_setprio 0
	s_barrier
	s_add_i32 s52, s52, s41
	v_lshl_add_u64 v[212:213], s[30:31], 0, v[202:203]
	s_mov_b32 m0, s52
	ds_read_b128 v[164:167], v253 offset:16384
	ds_read_b128 v[168:171], v253 offset:17408
	ds_read_b128 v[172:175], v253 offset:18432
	ds_read_b128 v[176:179], v253 offset:19456
	ds_read_b128 v[180:183], v253 offset:20480
	ds_read_b128 v[184:187], v253 offset:21504
	ds_read_b128 v[188:191], v253 offset:22528
	ds_read_b128 v[192:195], v253 offset:23552
	global_load_lds_dwordx4 v[212:213], off
	s_add_i32 m0, s52, 0x2000
	s_add_u32 s52, s30, 0x40000
	v_lshl_add_u64 v[214:215], s[30:31], 0, v[206:207]
	s_addc_u32 s53, s31, 0
	s_add_i32 s54, s54, s41
	global_load_lds_dwordx4 v[214:215], off
	v_lshl_add_u64 v[216:217], s[52:53], 0, v[202:203]
	s_mov_b32 m0, s54
	v_lshl_add_u64 v[218:219], s[34:35], 0, v[204:205]
	global_load_lds_dwordx4 v[216:217], off
	s_add_i32 m0, s54, 0x2000
	v_lshl_add_u64 v[216:217], s[52:53], 0, v[206:207]
	global_load_lds_dwordx4 v[216:217], off
	s_mov_b32 m0, s42
	v_lshl_add_u64 v[216:217], s[34:35], 0, v[0:1]
	global_load_lds_dwordx4 v[216:217], off
	s_mov_b32 m0, s43
	s_add_i32 s52, 0, 0x18000
	global_load_lds_dwordx4 v[218:219], off
	s_waitcnt vmcnt(8) lgkmcnt(0)
	s_barrier
; #define PG8_STAGE(bufoff, gbase, voff) do { _Pragma("unroll") for (int _i = 0; _i < 2; ++_i) \
;         __builtin_amdgcn_global_load_lds((const unsigned*)((const char*)(gbase) + (voff)[_i]), (PG8_LAS unsigned*)(lds + (bufoff) + ldsw + _i * 8192), 16, 0, 0); } while (0)
; #define PG8_LDA(dst, b, h) do { _Pragma("unroll") for (int m = 0; m < 4; ++m) _Pragma("unroll") for (int k = 0; k < 2; ++k) dst[m][k] = *(const PG8_LAS bf16x8*)(lds + PG8_SA(b, h) + aoff + m * 2048 + k * 1024); } while (0)
; #define PG8_LDB(dst, b, h) do { _Pragma("unroll") for (int n = 0; n < 2; ++n) _Pragma("unroll") for (int k = 0; k < 2; ++k) dst[n][k] = *(const PG8_LAS bf16x8*)(lds + PG8_SB(b, h) + boff + n * 2048 + k * 1024); } while (0)
; #define PG8_MMA(ai, bj, At, Bt) do { __builtin_amdgcn_s_setprio(1); _Pragma("unroll") for (int m = 0; m < 4; ++m) _Pragma("unroll") for (int n = 0; n < 2; ++n) _Pragma("unroll") for (int k = 0; k < 2; ++k) \
;         acc[ai][bj][m][n] = __builtin_amdgcn_mfma_f32_16x16x32_bf16(Bt[n][k], At[m][k], acc[ai][bj][m][n], 0, 0, 0); __builtin_amdgcn_s_setprio(0); } while (0)
; #define PG8_WAIT_V(n) asm volatile("s_waitcnt vmcnt(" #n ")" ::: "memory")
; #define PG8_WAIT_L(n) asm volatile("s_waitcnt lgkmcnt(" #n ")" ::: "memory")
; #define PG8_BAR __builtin_amdgcn_s_barrier()
; #define PG8_SCHED __builtin_amdgcn_sched_barrier(0)
; template <class Epi, class Sched, bool ALIGN_EPI = false, bool SP2 = false>
; __device__ __forceinline__ void gemm_phase(PG8_LAS unsigned char* lds, const Gemm g, const Sched& S, const Epi& E) {
;     ...
;             PG8_WAIT_V(8); PG8_WAIT_L(0); PG8_BAR; PG8_MMA(1, 0, At, B0); PG8_MMA(1, 1, At, B1); PG8_BAR; PG8_SCHED;
;             PG8_LDB(B0, 1, 0); PG8_LDB(B1, 1, 1); PG8_SCHED; PG8_LDA(At, 1, 0); PG8_STAGE(PG8_SA(0, 1), a2 + hstep, voffA);
;             PG8_WAIT_V(8); PG8_WAIT_L(0); PG8_BAR; PG8_MMA(0, 0, At, B0); PG8_MMA(0, 1, At, B1); PG8_BAR; PG8_SCHED;
	s_setprio 1
	v_mfma_f32_16x16x32_bf16 v[64:67], v[108:111], v[164:167], v[64:67]
	v_mfma_f32_16x16x32_bf16 v[60:63], v[124:127], v[164:167], v[60:63]
	v_mfma_f32_16x16x32_bf16 v[48:51], v[108:111], v[172:175], v[48:51]
	v_mfma_f32_16x16x32_bf16 v[44:47], v[124:127], v[172:175], v[44:47]
	v_mfma_f32_16x16x32_bf16 v[32:35], v[108:111], v[180:183], v[32:35]
	v_mfma_f32_16x16x32_bf16 v[28:31], v[124:127], v[180:183], v[28:31]
	v_mfma_f32_16x16x32_bf16 v[16:19], v[108:111], v[188:191], v[16:19]
	v_mfma_f32_16x16x32_bf16 v[12:15], v[124:127], v[188:191], v[12:15]
	v_mfma_f32_16x16x32_bf16 v[64:67], v[112:115], v[168:171], v[64:67]
	v_mfma_f32_16x16x32_bf16 v[60:63], v[128:131], v[168:171], v[60:63]
	v_mfma_f32_16x16x32_bf16 v[48:51], v[112:115], v[176:179], v[48:51]
	v_mfma_f32_16x16x32_bf16 v[44:47], v[128:131], v[176:179], v[44:47]
	v_mfma_f32_16x16x32_bf16 v[32:35], v[112:115], v[184:187], v[32:35]
	v_mfma_f32_16x16x32_bf16 v[28:31], v[128:131], v[184:187], v[28:31]
	v_mfma_f32_16x16x32_bf16 v[16:19], v[112:115], v[192:195], v[16:19]
	v_mfma_f32_16x16x32_bf16 v[12:15], v[128:131], v[192:195], v[12:15]
	v_mfma_f32_16x16x32_bf16 v[56:59], v[132:135], v[164:167], v[56:59]
	v_mfma_f32_16x16x32_bf16 v[52:55], v[148:151], v[164:167], v[52:55]
	v_mfma_f32_16x16x32_bf16 v[40:43], v[132:135], v[172:175], v[40:43]
	v_mfma_f32_16x16x32_bf16 v[36:39], v[148:151], v[172:175], v[36:39]
	v_mfma_f32_16x16x32_bf16 v[24:27], v[132:135], v[180:183], v[24:27]
	v_mfma_f32_16x16x32_bf16 v[20:23], v[148:151], v[180:183], v[20:23]
	v_mfma_f32_16x16x32_bf16 v[8:11], v[132:135], v[188:191], v[8:11]
	v_mfma_f32_16x16x32_bf16 v[4:7], v[148:151], v[188:191], v[4:7]
	v_mfma_f32_16x16x32_bf16 v[56:59], v[140:143], v[168:171], v[56:59]
	v_mfma_f32_16x16x32_bf16 v[52:55], v[156:159], v[168:171], v[52:55]
	v_mfma_f32_16x16x32_bf16 v[40:43], v[140:143], v[176:179], v[40:43]
	v_mfma_f32_16x16x32_bf16 v[36:39], v[156:159], v[176:179], v[36:39]
	v_mfma_f32_16x16x32_bf16 v[24:27], v[140:143], v[184:187], v[24:27]
	v_mfma_f32_16x16x32_bf16 v[20:23], v[156:159], v[184:187], v[20:23]
	v_mfma_f32_16x16x32_bf16 v[8:11], v[140:143], v[192:195], v[8:11]
	v_mfma_f32_16x16x32_bf16 v[4:7], v[156:159], v[192:195], v[4:7]
	s_setprio 0
	s_barrier
	s_add_i32 s53, 0, 0x1c000
	v_add_u32_e32 v128, s52, v251
	v_add_u32_e32 v156, s53, v251
	ds_read_b128 v[108:111], v128
	ds_read_b128 v[112:115], v128 offset:1024
	ds_read_b128 v[124:127], v128 offset:2048
	ds_read_b128 v[128:131], v128 offset:3072
	ds_read_b128 v[132:135], v156
	ds_read_b128 v[140:143], v156 offset:1024
	ds_read_b128 v[148:151], v156 offset:2048
	ds_read_b128 v[156:159], v156 offset:3072
	s_add_u32 s34, s34, 0x40000
	s_addc_u32 s35, s35, 0
	s_mov_b32 m0, s46
	v_lshl_add_u64 v[220:221], s[34:35], 0, v[0:1]
	ds_read_b128 v[164:167], v253 offset:32768
	ds_read_b128 v[168:171], v253 offset:33792
	ds_read_b128 v[172:175], v253 offset:34816
	ds_read_b128 v[176:179], v253 offset:35840
	ds_read_b128 v[180:183], v253 offset:36864
	ds_read_b128 v[184:187], v253 offset:37888
	ds_read_b128 v[188:191], v253 offset:38912
	ds_read_b128 v[192:195], v253 offset:39936
	global_load_lds_dwordx4 v[220:221], off
	s_mov_b32 m0, s47
	v_lshl_add_u64 v[220:221], s[34:35], 0, v[204:205]
	global_load_lds_dwordx4 v[220:221], off
	s_waitcnt vmcnt(8) lgkmcnt(0)
	s_barrier
	s_setprio 1
	v_mfma_f32_16x16x32_bf16 v[160:163], v[108:111], v[164:167], v[160:163]
	v_mfma_f32_16x16x32_bf16 v[152:155], v[124:127], v[164:167], v[152:155]
	v_mfma_f32_16x16x32_bf16 v[120:123], v[108:111], v[172:175], v[120:123]
	v_mfma_f32_16x16x32_bf16 v[116:119], v[124:127], v[172:175], v[116:119]
	v_mfma_f32_16x16x32_bf16 v[96:99], v[108:111], v[180:183], v[96:99]
	v_mfma_f32_16x16x32_bf16 v[92:95], v[124:127], v[180:183], v[92:95]
	v_mfma_f32_16x16x32_bf16 v[80:83], v[108:111], v[188:191], v[80:83]
	v_mfma_f32_16x16x32_bf16 v[76:79], v[124:127], v[188:191], v[76:79]
	v_mfma_f32_16x16x32_bf16 v[160:163], v[112:115], v[168:171], v[160:163]
	v_mfma_f32_16x16x32_bf16 v[152:155], v[128:131], v[168:171], v[152:155]
	v_mfma_f32_16x16x32_bf16 v[120:123], v[112:115], v[176:179], v[120:123]
	v_mfma_f32_16x16x32_bf16 v[116:119], v[128:131], v[176:179], v[116:119]
	v_mfma_f32_16x16x32_bf16 v[96:99], v[112:115], v[184:187], v[96:99]
	v_mfma_f32_16x16x32_bf16 v[92:95], v[128:131], v[184:187], v[92:95]
	v_mfma_f32_16x16x32_bf16 v[80:83], v[112:115], v[192:195], v[80:83]
	v_mfma_f32_16x16x32_bf16 v[76:79], v[128:131], v[192:195], v[76:79]
	v_mfma_f32_16x16x32_bf16 v[144:147], v[132:135], v[164:167], v[144:147]
	v_mfma_f32_16x16x32_bf16 v[136:139], v[148:151], v[164:167], v[136:139]
	v_mfma_f32_16x16x32_bf16 v[104:107], v[132:135], v[172:175], v[104:107]
	v_mfma_f32_16x16x32_bf16 v[100:103], v[148:151], v[172:175], v[100:103]
	v_mfma_f32_16x16x32_bf16 v[88:91], v[132:135], v[180:183], v[88:91]
	v_mfma_f32_16x16x32_bf16 v[84:87], v[148:151], v[180:183], v[84:87]
	v_mfma_f32_16x16x32_bf16 v[72:75], v[132:135], v[188:191], v[72:75]
	v_mfma_f32_16x16x32_bf16 v[68:71], v[148:151], v[188:191], v[68:71]
	v_mfma_f32_16x16x32_bf16 v[144:147], v[140:143], v[168:171], v[144:147]
	v_mfma_f32_16x16x32_bf16 v[136:139], v[156:159], v[168:171], v[136:139]
	v_mfma_f32_16x16x32_bf16 v[104:107], v[140:143], v[176:179], v[104:107]
	v_mfma_f32_16x16x32_bf16 v[100:103], v[156:159], v[176:179], v[100:103]
	v_mfma_f32_16x16x32_bf16 v[88:91], v[140:143], v[184:187], v[88:91]
	v_mfma_f32_16x16x32_bf16 v[84:87], v[156:159], v[184:187], v[84:87]
	v_mfma_f32_16x16x32_bf16 v[72:75], v[140:143], v[192:195], v[72:75]
	v_mfma_f32_16x16x32_bf16 v[68:71], v[156:159], v[192:195], v[68:71]
	s_setprio 0
	s_barrier
; #define PG8_STAGE(bufoff, gbase, voff) do { _Pragma("unroll") for (int _i = 0; _i < 2; ++_i) \
;         __builtin_amdgcn_global_load_lds((const unsigned*)((const char*)(gbase) + (voff)[_i]), (PG8_LAS unsigned*)(lds + (bufoff) + ldsw + _i * 8192), 16, 0, 0); } while (0)
; #define PG8_LDA(dst, b, h) do { _Pragma("unroll") for (int m = 0; m < 4; ++m) _Pragma("unroll") for (int k = 0; k < 2; ++k) dst[m][k] = *(const PG8_LAS bf16x8*)(lds + PG8_SA(b, h) + aoff + m * 2048 + k * 1024); } while (0)
; #define PG8_MMA(ai, bj, At, Bt) do { __builtin_amdgcn_s_setprio(1); _Pragma("unroll") for (int m = 0; m < 4; ++m) _Pragma("unroll") for (int n = 0; n < 2; ++n) _Pragma("unroll") for (int k = 0; k < 2; ++k) \
;         acc[ai][bj][m][n] = __builtin_amdgcn_mfma_f32_16x16x32_bf16(Bt[n][k], At[m][k], acc[ai][bj][m][n], 0, 0, 0); __builtin_amdgcn_s_setprio(0); } while (0)
; #define PG8_WAIT_V(n) asm volatile("s_waitcnt vmcnt(" #n ")" ::: "memory")
; #define PG8_WAIT_L(n) asm volatile("s_waitcnt lgkmcnt(" #n ")" ::: "memory")
; #define PG8_BAR __builtin_amdgcn_s_barrier()
; #define PG8_SCHED __builtin_amdgcn_sched_barrier(0)
; template <class Epi, class Sched, bool ALIGN_EPI = false, bool SP2 = false>
; __device__ __forceinline__ void gemm_phase(PG8_LAS unsigned char* lds, const Gemm g, const Sched& S, const Epi& E) {
;     ...
;         for (int t = 0; t < nt; t += 2) {
;             const bool last = (t == nt - 2);
;             const char* a1 = cA + (size_t)(t + 1) * kstep;
;             const char* a2 = last ? nA : cA + (size_t)(t + 2) * kstep; const char* b2 = last ? nB : cB + (size_t)(t + 2) * kstep;
;     ...
;             PG8_LDA(At, 1, 1); PG8_STAGE(PG8_SB(1, 0), b3, voffB); PG8_STAGE(PG8_SB(1, 1), b3 + hstep, voffB); PG8_STAGE(PG8_SA(1, 0), a3, voffA);
;             PG8_WAIT_V(8); PG8_WAIT_L(0); PG8_BAR; PG8_MMA(1, 0, At, B0); PG8_MMA(1, 1, At, B1); PG8_BAR; PG8_SCHED;
	s_add_i32 s34, s52, s41
	v_lshl_add_u64 v[212:213], v[212:213], 0, s[82:83]
	s_mov_b32 m0, s34
	ds_read_b128 v[164:167], v253 offset:49152
	ds_read_b128 v[168:171], v253 offset:50176
	ds_read_b128 v[172:175], v253 offset:51200
	ds_read_b128 v[176:179], v253 offset:52224
	ds_read_b128 v[180:183], v253 offset:53248
	ds_read_b128 v[184:187], v253 offset:54272
	ds_read_b128 v[188:191], v253 offset:55296
	ds_read_b128 v[192:195], v253 offset:56320
	global_load_lds_dwordx4 v[212:213], off
	s_add_i32 m0, s34, 0x2000
	s_add_u32 s30, s30, 0x40080
	v_lshl_add_u64 v[212:213], v[214:215], 0, s[82:83]
	s_addc_u32 s31, s31, 0
	s_add_i32 s34, s53, s41
	global_load_lds_dwordx4 v[212:213], off
	s_mov_b32 m0, s34
	v_lshl_add_u64 v[212:213], s[30:31], 0, v[202:203]
	global_load_lds_dwordx4 v[212:213], off
	s_add_i32 m0, s34, 0x2000
	v_lshl_add_u64 v[212:213], s[30:31], 0, v[206:207]
	global_load_lds_dwordx4 v[212:213], off
	s_mov_b32 m0, s49
	v_lshl_add_u64 v[212:213], v[216:217], 0, s[82:83]
	global_load_lds_dwordx4 v[212:213], off
	s_mov_b32 m0, s50
	v_lshl_add_u64 v[212:213], v[218:219], 0, s[82:83]
	global_load_lds_dwordx4 v[212:213], off
	s_waitcnt vmcnt(8) lgkmcnt(0)
	s_barrier
	s_setprio 1
	v_mfma_f32_16x16x32_bf16 v[64:67], v[108:111], v[164:167], v[64:67]
	v_mfma_f32_16x16x32_bf16 v[60:63], v[124:127], v[164:167], v[60:63]
	v_mfma_f32_16x16x32_bf16 v[48:51], v[108:111], v[172:175], v[48:51]
	v_mfma_f32_16x16x32_bf16 v[44:47], v[124:127], v[172:175], v[44:47]
	v_mfma_f32_16x16x32_bf16 v[32:35], v[108:111], v[180:183], v[32:35]
	v_mfma_f32_16x16x32_bf16 v[28:31], v[124:127], v[180:183], v[28:31]
	v_mfma_f32_16x16x32_bf16 v[16:19], v[108:111], v[188:191], v[16:19]
	v_mfma_f32_16x16x32_bf16 v[12:15], v[124:127], v[188:191], v[12:15]
	v_mfma_f32_16x16x32_bf16 v[64:67], v[112:115], v[168:171], v[64:67]
	v_mfma_f32_16x16x32_bf16 v[60:63], v[128:131], v[168:171], v[60:63]
	v_mfma_f32_16x16x32_bf16 v[48:51], v[112:115], v[176:179], v[48:51]
	v_mfma_f32_16x16x32_bf16 v[44:47], v[128:131], v[176:179], v[44:47]
	v_mfma_f32_16x16x32_bf16 v[32:35], v[112:115], v[184:187], v[32:35]
	v_mfma_f32_16x16x32_bf16 v[28:31], v[128:131], v[184:187], v[28:31]
	v_mfma_f32_16x16x32_bf16 v[16:19], v[112:115], v[192:195], v[16:19]
	v_mfma_f32_16x16x32_bf16 v[12:15], v[128:131], v[192:195], v[12:15]
	v_mfma_f32_16x16x32_bf16 v[56:59], v[132:135], v[164:167], v[56:59]
	v_mfma_f32_16x16x32_bf16 v[52:55], v[148:151], v[164:167], v[52:55]
	v_mfma_f32_16x16x32_bf16 v[40:43], v[132:135], v[172:175], v[40:43]
	v_mfma_f32_16x16x32_bf16 v[36:39], v[148:151], v[172:175], v[36:39]
	v_mfma_f32_16x16x32_bf16 v[24:27], v[132:135], v[180:183], v[24:27]
	v_mfma_f32_16x16x32_bf16 v[20:23], v[148:151], v[180:183], v[20:23]
	v_mfma_f32_16x16x32_bf16 v[8:11], v[132:135], v[188:191], v[8:11]
	v_mfma_f32_16x16x32_bf16 v[4:7], v[148:151], v[188:191], v[4:7]
	v_mfma_f32_16x16x32_bf16 v[56:59], v[140:143], v[168:171], v[56:59]
	v_mfma_f32_16x16x32_bf16 v[52:55], v[156:159], v[168:171], v[52:55]
	v_mfma_f32_16x16x32_bf16 v[40:43], v[140:143], v[176:179], v[40:43]
	v_mfma_f32_16x16x32_bf16 v[36:39], v[156:159], v[176:179], v[36:39]
	v_mfma_f32_16x16x32_bf16 v[24:27], v[140:143], v[184:187], v[24:27]
	v_mfma_f32_16x16x32_bf16 v[20:23], v[156:159], v[184:187], v[20:23]
	v_mfma_f32_16x16x32_bf16 v[8:11], v[140:143], v[192:195], v[8:11]
	v_mfma_f32_16x16x32_bf16 v[4:7], v[156:159], v[192:195], v[4:7]
	s_setprio 0
	s_barrier
	s_add_i32 s45, s45, 2
	s_add_u32 s28, s28, 0x100
	s_addc_u32 s29, s29, 0
	s_add_u32 s27, s27, 0x100
	s_addc_u32 s44, s44, 0
	s_cmp_gt_u32 s45, 13
	s_cbranch_scc0 .LBB0_329
	s_and_b64 vcc, exec, s[14:15]
	s_cbranch_vccz .LBB0_332
	s_barrier

; #define PG8_STAGE(bufoff, gbase, voff) do { _Pragma("unroll") for (int _i = 0; _i < 2; ++_i) \
;         __builtin_amdgcn_global_load_lds((const unsigned*)((const char*)(gbase) + (voff)[_i]), (PG8_LAS unsigned*)(lds + (bufoff) + ldsw + _i * 8192), 16, 0, 0); } while (0)
; #define PG8_LDA(dst, b, h) do { _Pragma("unroll") for (int m = 0; m < 4; ++m) _Pragma("unroll") for (int k = 0; k < 2; ++k) dst[m][k] = *(const PG8_LAS bf16x8*)(lds + PG8_SA(b, h) + aoff + m * 2048 + k * 1024); } while (0)
; #define PG8_LDB(dst, b, h) do { _Pragma("unroll") for (int n = 0; n < 2; ++n) _Pragma("unroll") for (int k = 0; k < 2; ++k) dst[n][k] = *(const PG8_LAS bf16x8*)(lds + PG8_SB(b, h) + boff + n * 2048 + k * 1024); } while (0)
; #define PG8_MMA(ai, bj, At, Bt) do { __builtin_amdgcn_s_setprio(1); _Pragma("unroll") for (int m = 0; m < 4; ++m) _Pragma("unroll") for (int n = 0; n < 2; ++n) _Pragma("unroll") for (int k = 0; k < 2; ++k) \
;         acc[ai][bj][m][n] = __builtin_amdgcn_mfma_f32_16x16x32_bf16(Bt[n][k], At[m][k], acc[ai][bj][m][n], 0, 0, 0); __builtin_amdgcn_s_setprio(0); } while (0)
; #define PG8_WAIT_V(n) asm volatile("s_waitcnt vmcnt(" #n ")" ::: "memory")
; #define PG8_WAIT_L(n) asm volatile("s_waitcnt lgkmcnt(" #n ")" ::: "memory")
; #define PG8_BAR __builtin_amdgcn_s_barrier()
; #define PG8_SCHED __builtin_amdgcn_sched_barrier(0)
; template <class Epi, class Sched, bool ALIGN_EPI = false, bool SP2 = false>
; __device__ __forceinline__ void gemm_phase(PG8_LAS unsigned char* lds, const Gemm g, const Sched& S, const Epi& E) {
;     ...
;         for (int t = 0; t < nt; t += 2) {
;             const bool last = (t == nt - 2);
;             const char* a1 = cA + (size_t)(t + 1) * kstep;
;             const char* a2 = last ? nA : cA + (size_t)(t + 2) * kstep; const char* b2 = last ? nB : cB + (size_t)(t + 2) * kstep;
;             const char* a3 = a2 + kstep; const char* b3 = b2 + kstep;
;             if (last && has_next) S.a_ready(nxt);
;             if constexpr (SP2) {
;             PG8_LDB(B0, 0, 0); PG8_LDB(B1, 0, 1); PG8_SCHED; PG8_LDA(At, 0, 0); PG8_STAGE(PG8_SA(1, 1), a1 + hstep, voffA);
;             PG8_WAIT_V(8); PG8_WAIT_L(0); PG8_BAR; PG8_MMA(0, 0, At, B0); PG8_MMA(0, 1, At, B1); PG8_BAR; PG8_SCHED;
;             PG8_LDA(At, 0, 1); PG8_STAGE(PG8_SB(0, 0), b2, voffB); PG8_STAGE(PG8_SB(0, 1), b2 + hstep, voffB); PG8_STAGE(PG8_SA(0, 0), a2, voffA);
.LBB0_405:
	s_add_u32 s24, s8, 0xfffc0080
	s_addc_u32 s25, s9, -1
	s_add_i32 s47, 0, 0x10000
	s_cmp_eq_u32 s46, 12
	s_cselect_b32 s27, s7, s25
	s_cselect_b32 s26, s17, s24
	s_cselect_b32 s25, s19, s45
	s_cselect_b32 s24, s43, s44
	s_add_i32 s50, 0, 0x14000
	v_add_u32_e32 v156, s47, v164
	v_add_u32_e32 v167, s50, v164
	ds_read_b128 v[144:147], v156
	ds_read_b128 v[148:151], v156 offset:1024
	ds_read_b128 v[152:155], v156 offset:2048
	ds_read_b128 v[156:159], v156 offset:3072
	ds_read_b128 v[160:163], v167
	ds_read_b128 v[168:171], v167 offset:1024
	ds_read_b128 v[172:175], v167 offset:2048
	ds_read_b128 v[176:179], v167 offset:3072
	v_lshl_add_u64 v[198:199], s[8:9], 0, v[140:141]
	s_add_i32 m0, s37, 0xc000
	ds_read_b128 v[180:183], v166
	ds_read_b128 v[184:187], v166 offset:1024
	ds_read_b128 v[188:191], v166 offset:2048
	ds_read_b128 v[192:195], v166 offset:3072
	ds_read_b128 v[202:205], v166 offset:4096
	ds_read_b128 v[206:209], v166 offset:5120
	ds_read_b128 v[210:213], v166 offset:6144
	ds_read_b128 v[214:217], v166 offset:7168
	global_load_lds_dwordx4 v[198:199], off
	s_add_i32 m0, s37, 0xe000
	v_lshl_add_u64 v[198:199], s[8:9], 0, v[142:143]
	global_load_lds_dwordx4 v[198:199], off
	s_waitcnt vmcnt(8) lgkmcnt(0)
	s_barrier
	s_setprio 1
	v_mfma_f32_16x16x32_bf16 v[128:131], v[144:147], v[180:183], v[128:131]
	v_mfma_f32_16x16x32_bf16 v[120:123], v[152:155], v[180:183], v[120:123]
	v_mfma_f32_16x16x32_bf16 v[112:115], v[144:147], v[188:191], v[112:115]
	v_mfma_f32_16x16x32_bf16 v[104:107], v[152:155], v[188:191], v[104:107]
	v_mfma_f32_16x16x32_bf16 v[96:99], v[144:147], v[202:205], v[96:99]
	v_mfma_f32_16x16x32_bf16 v[88:91], v[152:155], v[202:205], v[88:91]
	v_mfma_f32_16x16x32_bf16 v[80:83], v[144:147], v[210:213], v[80:83]
	v_mfma_f32_16x16x32_bf16 v[72:75], v[152:155], v[210:213], v[72:75]
	v_mfma_f32_16x16x32_bf16 v[128:131], v[148:151], v[184:187], v[128:131]
	v_mfma_f32_16x16x32_bf16 v[120:123], v[156:159], v[184:187], v[120:123]
	v_mfma_f32_16x16x32_bf16 v[112:115], v[148:151], v[192:195], v[112:115]
	v_mfma_f32_16x16x32_bf16 v[104:107], v[156:159], v[192:195], v[104:107]
	v_mfma_f32_16x16x32_bf16 v[96:99], v[148:151], v[206:209], v[96:99]
	v_mfma_f32_16x16x32_bf16 v[88:91], v[156:159], v[206:209], v[88:91]
	v_mfma_f32_16x16x32_bf16 v[80:83], v[148:151], v[214:217], v[80:83]
	v_mfma_f32_16x16x32_bf16 v[72:75], v[156:159], v[214:217], v[72:75]
	v_mfma_f32_16x16x32_bf16 v[124:127], v[160:163], v[180:183], v[124:127]
	v_mfma_f32_16x16x32_bf16 v[116:119], v[172:175], v[180:183], v[116:119]
	v_mfma_f32_16x16x32_bf16 v[108:111], v[160:163], v[188:191], v[108:111]
	v_mfma_f32_16x16x32_bf16 v[100:103], v[172:175], v[188:191], v[100:103]
	v_mfma_f32_16x16x32_bf16 v[92:95], v[160:163], v[202:205], v[92:95]
	v_mfma_f32_16x16x32_bf16 v[84:87], v[172:175], v[202:205], v[84:87]
	v_mfma_f32_16x16x32_bf16 v[76:79], v[160:163], v[210:213], v[76:79]
	v_mfma_f32_16x16x32_bf16 v[68:71], v[172:175], v[210:213], v[68:71]
	v_mfma_f32_16x16x32_bf16 v[124:127], v[168:171], v[184:187], v[124:127]
	v_mfma_f32_16x16x32_bf16 v[116:119], v[176:179], v[184:187], v[116:119]
	v_mfma_f32_16x16x32_bf16 v[108:111], v[168:171], v[192:195], v[108:111]
	v_mfma_f32_16x16x32_bf16 v[100:103], v[176:179], v[192:195], v[100:103]
	v_mfma_f32_16x16x32_bf16 v[92:95], v[168:171], v[206:209], v[92:95]
	v_mfma_f32_16x16x32_bf16 v[84:87], v[176:179], v[206:209], v[84:87]
	v_mfma_f32_16x16x32_bf16 v[76:79], v[168:171], v[214:217], v[76:79]
	v_mfma_f32_16x16x32_bf16 v[68:71], v[176:179], v[214:217], v[68:71]
	s_setprio 0
	s_barrier
	s_add_i32 s47, s47, s35
	v_lshl_add_u64 v[198:199], s[24:25], 0, v[134:135]
	s_mov_b32 m0, s47
	ds_read_b128 v[180:183], v166 offset:16384
	ds_read_b128 v[184:187], v166 offset:17408
	ds_read_b128 v[188:191], v166 offset:18432
	ds_read_b128 v[192:195], v166 offset:19456
	ds_read_b128 v[202:205], v166 offset:20480
	ds_read_b128 v[206:209], v166 offset:21504
	ds_read_b128 v[210:213], v166 offset:22528
	ds_read_b128 v[214:217], v166 offset:23552
	global_load_lds_dwordx4 v[198:199], off
	s_add_i32 m0, s47, 0x2000
	s_add_u32 s48, s24, 0x40000
	v_lshl_add_u64 v[218:219], s[24:25], 0, v[0:1]
	s_addc_u32 s49, s25, 0
	s_add_i32 s47, s50, s35
	global_load_lds_dwordx4 v[218:219], off
	v_lshl_add_u64 v[220:221], s[48:49], 0, v[134:135]
	s_mov_b32 m0, s47
	v_lshl_add_u64 v[222:223], s[26:27], 0, v[132:133]
	global_load_lds_dwordx4 v[220:221], off
	s_add_i32 m0, s47, 0x2000
	v_lshl_add_u64 v[220:221], s[48:49], 0, v[0:1]
	global_load_lds_dwordx4 v[220:221], off
	s_mov_b32 m0, s37
	v_lshl_add_u64 v[220:221], s[26:27], 0, v[136:137]
	global_load_lds_dwordx4 v[220:221], off
	s_mov_b32 m0, s38
	s_add_i32 s47, 0, 0x18000
	global_load_lds_dwordx4 v[222:223], off
	s_waitcnt vmcnt(8) lgkmcnt(0)
	s_barrier
; #define PG8_STAGE(bufoff, gbase, voff) do { _Pragma("unroll") for (int _i = 0; _i < 2; ++_i) \
;         __builtin_amdgcn_global_load_lds((const unsigned*)((const char*)(gbase) + (voff)[_i]), (PG8_LAS unsigned*)(lds + (bufoff) + ldsw + _i * 8192), 16, 0, 0); } while (0)
; #define PG8_LDA(dst, b, h) do { _Pragma("unroll") for (int m = 0; m < 4; ++m) _Pragma("unroll") for (int k = 0; k < 2; ++k) dst[m][k] = *(const PG8_LAS bf16x8*)(lds + PG8_SA(b, h) + aoff + m * 2048 + k * 1024); } while (0)
; #define PG8_LDB(dst, b, h) do { _Pragma("unroll") for (int n = 0; n < 2; ++n) _Pragma("unroll") for (int k = 0; k < 2; ++k) dst[n][k] = *(const PG8_LAS bf16x8*)(lds + PG8_SB(b, h) + boff + n * 2048 + k * 1024); } while (0)
; #define PG8_MMA(ai, bj, At, Bt) do { __builtin_amdgcn_s_setprio(1); _Pragma("unroll") for (int m = 0; m < 4; ++m) _Pragma("unroll") for (int n = 0; n < 2; ++n) _Pragma("unroll") for (int k = 0; k < 2; ++k) \
;         acc[ai][bj][m][n] = __builtin_amdgcn_mfma_f32_16x16x32_bf16(Bt[n][k], At[m][k], acc[ai][bj][m][n], 0, 0, 0); __builtin_amdgcn_s_setprio(0); } while (0)
; #define PG8_WAIT_V(n) asm volatile("s_waitcnt vmcnt(" #n ")" ::: "memory")
; #define PG8_WAIT_L(n) asm volatile("s_waitcnt lgkmcnt(" #n ")" ::: "memory")
; #define PG8_BAR __builtin_amdgcn_s_barrier()
; #define PG8_SCHED __builtin_amdgcn_sched_barrier(0)
; template <class Epi, class Sched, bool ALIGN_EPI = false, bool SP2 = false>
; __device__ __forceinline__ void gemm_phase(PG8_LAS unsigned char* lds, const Gemm g, const Sched& S, const Epi& E) {
;     ...
;             PG8_WAIT_V(8); PG8_WAIT_L(0); PG8_BAR; PG8_MMA(1, 0, At, B0); PG8_MMA(1, 1, At, B1); PG8_BAR; PG8_SCHED;
;             PG8_LDB(B0, 1, 0); PG8_LDB(B1, 1, 1); PG8_SCHED; PG8_LDA(At, 1, 0); PG8_STAGE(PG8_SA(0, 1), a2 + hstep, voffA);
;             PG8_WAIT_V(8); PG8_WAIT_L(0); PG8_BAR; PG8_MMA(0, 0, At, B0); PG8_MMA(0, 1, At, B1); PG8_BAR; PG8_SCHED;
	s_setprio 1
	v_mfma_f32_16x16x32_bf16 v[64:67], v[144:147], v[180:183], v[64:67]
	v_mfma_f32_16x16x32_bf16 v[56:59], v[152:155], v[180:183], v[56:59]
	v_mfma_f32_16x16x32_bf16 v[48:51], v[144:147], v[188:191], v[48:51]
	v_mfma_f32_16x16x32_bf16 v[40:43], v[152:155], v[188:191], v[40:43]
	v_mfma_f32_16x16x32_bf16 v[32:35], v[144:147], v[202:205], v[32:35]
	v_mfma_f32_16x16x32_bf16 v[24:27], v[152:155], v[202:205], v[24:27]
	v_mfma_f32_16x16x32_bf16 v[16:19], v[144:147], v[210:213], v[16:19]
	v_mfma_f32_16x16x32_bf16 v[8:11], v[152:155], v[210:213], v[8:11]
	v_mfma_f32_16x16x32_bf16 v[64:67], v[148:151], v[184:187], v[64:67]
	v_mfma_f32_16x16x32_bf16 v[56:59], v[156:159], v[184:187], v[56:59]
	v_mfma_f32_16x16x32_bf16 v[48:51], v[148:151], v[192:195], v[48:51]
	v_mfma_f32_16x16x32_bf16 v[40:43], v[156:159], v[192:195], v[40:43]
	v_mfma_f32_16x16x32_bf16 v[32:35], v[148:151], v[206:209], v[32:35]
	v_mfma_f32_16x16x32_bf16 v[24:27], v[156:159], v[206:209], v[24:27]
	v_mfma_f32_16x16x32_bf16 v[16:19], v[148:151], v[214:217], v[16:19]
	v_mfma_f32_16x16x32_bf16 v[8:11], v[156:159], v[214:217], v[8:11]
	v_mfma_f32_16x16x32_bf16 v[60:63], v[160:163], v[180:183], v[60:63]
	v_mfma_f32_16x16x32_bf16 v[52:55], v[172:175], v[180:183], v[52:55]
	v_mfma_f32_16x16x32_bf16 v[44:47], v[160:163], v[188:191], v[44:47]
	v_mfma_f32_16x16x32_bf16 v[36:39], v[172:175], v[188:191], v[36:39]
	v_mfma_f32_16x16x32_bf16 v[28:31], v[160:163], v[202:205], v[28:31]
	v_mfma_f32_16x16x32_bf16 v[20:23], v[172:175], v[202:205], v[20:23]
	v_mfma_f32_16x16x32_bf16 v[12:15], v[160:163], v[210:213], v[12:15]
	v_mfma_f32_16x16x32_bf16 v[4:7], v[172:175], v[210:213], v[4:7]
	v_mfma_f32_16x16x32_bf16 v[60:63], v[168:171], v[184:187], v[60:63]
	v_mfma_f32_16x16x32_bf16 v[52:55], v[176:179], v[184:187], v[52:55]
	v_mfma_f32_16x16x32_bf16 v[44:47], v[168:171], v[192:195], v[44:47]
	v_mfma_f32_16x16x32_bf16 v[36:39], v[176:179], v[192:195], v[36:39]
	v_mfma_f32_16x16x32_bf16 v[28:31], v[168:171], v[206:209], v[28:31]
	v_mfma_f32_16x16x32_bf16 v[20:23], v[176:179], v[206:209], v[20:23]
	v_mfma_f32_16x16x32_bf16 v[12:15], v[168:171], v[214:217], v[12:15]
	v_mfma_f32_16x16x32_bf16 v[4:7], v[176:179], v[214:217], v[4:7]
	s_setprio 0
	s_barrier
	s_add_i32 s48, 0, 0x1c000
	v_add_u32_e32 v156, s47, v164
	v_add_u32_e32 v167, s48, v164
	ds_read_b128 v[144:147], v156
	ds_read_b128 v[148:151], v156 offset:1024
	ds_read_b128 v[152:155], v156 offset:2048
	ds_read_b128 v[156:159], v156 offset:3072
	ds_read_b128 v[160:163], v167
	ds_read_b128 v[168:171], v167 offset:1024
	ds_read_b128 v[172:175], v167 offset:2048
	ds_read_b128 v[176:179], v167 offset:3072
	s_add_u32 s26, s26, 0x40000
	s_addc_u32 s27, s27, 0
	s_mov_b32 m0, s39
	v_lshl_add_u64 v[224:225], s[26:27], 0, v[136:137]
	ds_read_b128 v[180:183], v166 offset:32768
	ds_read_b128 v[184:187], v166 offset:33792
	ds_read_b128 v[188:191], v166 offset:34816
	ds_read_b128 v[192:195], v166 offset:35840
	ds_read_b128 v[202:205], v166 offset:36864
	ds_read_b128 v[206:209], v166 offset:37888
	ds_read_b128 v[210:213], v166 offset:38912
	ds_read_b128 v[214:217], v166 offset:39936
	global_load_lds_dwordx4 v[224:225], off
	s_mov_b32 m0, s40
	v_lshl_add_u64 v[224:225], s[26:27], 0, v[132:133]
	global_load_lds_dwordx4 v[224:225], off
	s_waitcnt vmcnt(8) lgkmcnt(0)
	s_barrier
	s_setprio 1
	v_mfma_f32_16x16x32_bf16 v[128:131], v[144:147], v[180:183], v[128:131]
	v_mfma_f32_16x16x32_bf16 v[120:123], v[152:155], v[180:183], v[120:123]
	v_mfma_f32_16x16x32_bf16 v[112:115], v[144:147], v[188:191], v[112:115]
	v_mfma_f32_16x16x32_bf16 v[104:107], v[152:155], v[188:191], v[104:107]
	v_mfma_f32_16x16x32_bf16 v[96:99], v[144:147], v[202:205], v[96:99]
	v_mfma_f32_16x16x32_bf16 v[88:91], v[152:155], v[202:205], v[88:91]
	v_mfma_f32_16x16x32_bf16 v[80:83], v[144:147], v[210:213], v[80:83]
	v_mfma_f32_16x16x32_bf16 v[72:75], v[152:155], v[210:213], v[72:75]
	v_mfma_f32_16x16x32_bf16 v[128:131], v[148:151], v[184:187], v[128:131]
	v_mfma_f32_16x16x32_bf16 v[120:123], v[156:159], v[184:187], v[120:123]
	v_mfma_f32_16x16x32_bf16 v[112:115], v[148:151], v[192:195], v[112:115]
	v_mfma_f32_16x16x32_bf16 v[104:107], v[156:159], v[192:195], v[104:107]
	v_mfma_f32_16x16x32_bf16 v[96:99], v[148:151], v[206:209], v[96:99]
	v_mfma_f32_16x16x32_bf16 v[88:91], v[156:159], v[206:209], v[88:91]
	v_mfma_f32_16x16x32_bf16 v[80:83], v[148:151], v[214:217], v[80:83]
	v_mfma_f32_16x16x32_bf16 v[72:75], v[156:159], v[214:217], v[72:75]
	v_mfma_f32_16x16x32_bf16 v[124:127], v[160:163], v[180:183], v[124:127]
	v_mfma_f32_16x16x32_bf16 v[116:119], v[172:175], v[180:183], v[116:119]
	v_mfma_f32_16x16x32_bf16 v[108:111], v[160:163], v[188:191], v[108:111]
	v_mfma_f32_16x16x32_bf16 v[100:103], v[172:175], v[188:191], v[100:103]
	v_mfma_f32_16x16x32_bf16 v[92:95], v[160:163], v[202:205], v[92:95]
	v_mfma_f32_16x16x32_bf16 v[84:87], v[172:175], v[202:205], v[84:87]
	v_mfma_f32_16x16x32_bf16 v[76:79], v[160:163], v[210:213], v[76:79]
	v_mfma_f32_16x16x32_bf16 v[68:71], v[172:175], v[210:213], v[68:71]
	v_mfma_f32_16x16x32_bf16 v[124:127], v[168:171], v[184:187], v[124:127]
	v_mfma_f32_16x16x32_bf16 v[116:119], v[176:179], v[184:187], v[116:119]
	v_mfma_f32_16x16x32_bf16 v[108:111], v[168:171], v[192:195], v[108:111]
	v_mfma_f32_16x16x32_bf16 v[100:103], v[176:179], v[192:195], v[100:103]
	v_mfma_f32_16x16x32_bf16 v[92:95], v[168:171], v[206:209], v[92:95]
	v_mfma_f32_16x16x32_bf16 v[84:87], v[176:179], v[206:209], v[84:87]
	v_mfma_f32_16x16x32_bf16 v[76:79], v[168:171], v[214:217], v[76:79]
	v_mfma_f32_16x16x32_bf16 v[68:71], v[176:179], v[214:217], v[68:71]
	s_setprio 0
	s_barrier
; #define PG8_STAGE(bufoff, gbase, voff) do { _Pragma("unroll") for (int _i = 0; _i < 2; ++_i) \
;         __builtin_amdgcn_global_load_lds((const unsigned*)((const char*)(gbase) + (voff)[_i]), (PG8_LAS unsigned*)(lds + (bufoff) + ldsw + _i * 8192), 16, 0, 0); } while (0)
; #define PG8_LDA(dst, b, h) do { _Pragma("unroll") for (int m = 0; m < 4; ++m) _Pragma("unroll") for (int k = 0; k < 2; ++k) dst[m][k] = *(const PG8_LAS bf16x8*)(lds + PG8_SA(b, h) + aoff + m * 2048 + k * 1024); } while (0)
; #define PG8_MMA(ai, bj, At, Bt) do { __builtin_amdgcn_s_setprio(1); _Pragma("unroll") for (int m = 0; m < 4; ++m) _Pragma("unroll") for (int n = 0; n < 2; ++n) _Pragma("unroll") for (int k = 0; k < 2; ++k) \
;         acc[ai][bj][m][n] = __builtin_amdgcn_mfma_f32_16x16x32_bf16(Bt[n][k], At[m][k], acc[ai][bj][m][n], 0, 0, 0); __builtin_amdgcn_s_setprio(0); } while (0)
; #define PG8_WAIT_V(n) asm volatile("s_waitcnt vmcnt(" #n ")" ::: "memory")
; #define PG8_WAIT_L(n) asm volatile("s_waitcnt lgkmcnt(" #n ")" ::: "memory")
; #define PG8_BAR __builtin_amdgcn_s_barrier()
; #define PG8_SCHED __builtin_amdgcn_sched_barrier(0)
; template <class Epi, class Sched, bool ALIGN_EPI = false, bool SP2 = false>
; __device__ __forceinline__ void gemm_phase(PG8_LAS unsigned char* lds, const Gemm g, const Sched& S, const Epi& E) {
;     ...
;         for (int t = 0; t < nt; t += 2) {
;             const bool last = (t == nt - 2);
;             const char* a1 = cA + (size_t)(t + 1) * kstep;
;             const char* a2 = last ? nA : cA + (size_t)(t + 2) * kstep; const char* b2 = last ? nB : cB + (size_t)(t + 2) * kstep;
;     ...
;             PG8_LDA(At, 1, 1); PG8_STAGE(PG8_SB(1, 0), b3, voffB); PG8_STAGE(PG8_SB(1, 1), b3 + hstep, voffB); PG8_STAGE(PG8_SA(1, 0), a3, voffA);
;             PG8_WAIT_V(8); PG8_WAIT_L(0); PG8_BAR; PG8_MMA(1, 0, At, B0); PG8_MMA(1, 1, At, B1); PG8_BAR; PG8_SCHED;
	s_add_i32 s26, s47, s35
	v_lshl_add_u64 v[198:199], v[198:199], 0, s[82:83]
	s_mov_b32 m0, s26
	ds_read_b128 v[180:183], v166 offset:49152
	ds_read_b128 v[184:187], v166 offset:50176
	ds_read_b128 v[188:191], v166 offset:51200
	ds_read_b128 v[192:195], v166 offset:52224
	ds_read_b128 v[202:205], v166 offset:53248
	ds_read_b128 v[206:209], v166 offset:54272
	ds_read_b128 v[210:213], v166 offset:55296
	ds_read_b128 v[214:217], v166 offset:56320
	global_load_lds_dwordx4 v[198:199], off
	s_add_i32 m0, s26, 0x2000
	s_add_u32 s24, s24, 0x40080
	v_lshl_add_u64 v[198:199], v[218:219], 0, s[82:83]
	s_addc_u32 s25, s25, 0
	s_add_i32 s26, s48, s35
	global_load_lds_dwordx4 v[198:199], off
	s_mov_b32 m0, s26
	v_lshl_add_u64 v[198:199], s[24:25], 0, v[134:135]
	global_load_lds_dwordx4 v[198:199], off
	s_add_i32 m0, s26, 0x2000
	v_lshl_add_u64 v[198:199], s[24:25], 0, v[0:1]
	global_load_lds_dwordx4 v[198:199], off
	s_mov_b32 m0, s41
	v_lshl_add_u64 v[198:199], v[220:221], 0, s[82:83]
	global_load_lds_dwordx4 v[198:199], off
	s_mov_b32 m0, s42
	v_lshl_add_u64 v[198:199], v[222:223], 0, s[82:83]
	global_load_lds_dwordx4 v[198:199], off
	s_waitcnt vmcnt(8) lgkmcnt(0)
	s_barrier
	s_setprio 1
	v_mfma_f32_16x16x32_bf16 v[64:67], v[144:147], v[180:183], v[64:67]
	v_mfma_f32_16x16x32_bf16 v[56:59], v[152:155], v[180:183], v[56:59]
	v_mfma_f32_16x16x32_bf16 v[48:51], v[144:147], v[188:191], v[48:51]
	v_mfma_f32_16x16x32_bf16 v[40:43], v[152:155], v[188:191], v[40:43]
	v_mfma_f32_16x16x32_bf16 v[32:35], v[144:147], v[202:205], v[32:35]
	v_mfma_f32_16x16x32_bf16 v[24:27], v[152:155], v[202:205], v[24:27]
	v_mfma_f32_16x16x32_bf16 v[16:19], v[144:147], v[210:213], v[16:19]
	v_mfma_f32_16x16x32_bf16 v[8:11], v[152:155], v[210:213], v[8:11]
	v_mfma_f32_16x16x32_bf16 v[64:67], v[148:151], v[184:187], v[64:67]
	v_mfma_f32_16x16x32_bf16 v[56:59], v[156:159], v[184:187], v[56:59]
	v_mfma_f32_16x16x32_bf16 v[48:51], v[148:151], v[192:195], v[48:51]
	v_mfma_f32_16x16x32_bf16 v[40:43], v[156:159], v[192:195], v[40:43]
	v_mfma_f32_16x16x32_bf16 v[32:35], v[148:151], v[206:209], v[32:35]
	v_mfma_f32_16x16x32_bf16 v[24:27], v[156:159], v[206:209], v[24:27]
	v_mfma_f32_16x16x32_bf16 v[16:19], v[148:151], v[214:217], v[16:19]
	v_mfma_f32_16x16x32_bf16 v[8:11], v[156:159], v[214:217], v[8:11]
	v_mfma_f32_16x16x32_bf16 v[60:63], v[160:163], v[180:183], v[60:63]
	v_mfma_f32_16x16x32_bf16 v[52:55], v[172:175], v[180:183], v[52:55]
	v_mfma_f32_16x16x32_bf16 v[44:47], v[160:163], v[188:191], v[44:47]
	v_mfma_f32_16x16x32_bf16 v[36:39], v[172:175], v[188:191], v[36:39]
	v_mfma_f32_16x16x32_bf16 v[28:31], v[160:163], v[202:205], v[28:31]
	v_mfma_f32_16x16x32_bf16 v[20:23], v[172:175], v[202:205], v[20:23]
	v_mfma_f32_16x16x32_bf16 v[12:15], v[160:163], v[210:213], v[12:15]
	v_mfma_f32_16x16x32_bf16 v[4:7], v[172:175], v[210:213], v[4:7]
	v_mfma_f32_16x16x32_bf16 v[60:63], v[168:171], v[184:187], v[60:63]
	v_mfma_f32_16x16x32_bf16 v[52:55], v[176:179], v[184:187], v[52:55]
	v_mfma_f32_16x16x32_bf16 v[44:47], v[168:171], v[192:195], v[44:47]
	v_mfma_f32_16x16x32_bf16 v[36:39], v[176:179], v[192:195], v[36:39]
	v_mfma_f32_16x16x32_bf16 v[28:31], v[168:171], v[206:209], v[28:31]
	v_mfma_f32_16x16x32_bf16 v[20:23], v[176:179], v[206:209], v[20:23]
	v_mfma_f32_16x16x32_bf16 v[12:15], v[168:171], v[214:217], v[12:15]
	v_mfma_f32_16x16x32_bf16 v[4:7], v[176:179], v[214:217], v[4:7]
	s_setprio 0
	s_barrier
	s_add_i32 s46, s46, 2
	s_add_u32 s8, s8, 0x100
	s_addc_u32 s9, s9, 0
	s_add_u32 s44, s44, 0x100
	s_addc_u32 s45, s45, 0
	s_cmp_gt_u32 s46, 13
	s_cbranch_scc0 .LBB0_405
	s_and_b64 vcc, exec, s[14:15]
	s_cbranch_vccz .LBB0_408
	s_barrier

; #define PG8_STAGE(bufoff, gbase, voff) do { _Pragma("unroll") for (int _i = 0; _i < 2; ++_i) \
;         __builtin_amdgcn_global_load_lds((const unsigned*)((const char*)(gbase) + (voff)[_i]), (PG8_LAS unsigned*)(lds + (bufoff) + ldsw + _i * 8192), 16, 0, 0); } while (0)
; #define PG8_LDA(dst, b, h) do { _Pragma("unroll") for (int m = 0; m < 4; ++m) _Pragma("unroll") for (int k = 0; k < 2; ++k) dst[m][k] = *(const PG8_LAS bf16x8*)(lds + PG8_SA(b, h) + aoff + m * 2048 + k * 1024); } while (0)
; #define PG8_LDB(dst, b, h) do { _Pragma("unroll") for (int n = 0; n < 2; ++n) _Pragma("unroll") for (int k = 0; k < 2; ++k) dst[n][k] = *(const PG8_LAS bf16x8*)(lds + PG8_SB(b, h) + boff + n * 2048 + k * 1024); } while (0)
; #define PG8_MMA(ai, bj, At, Bt) do { __builtin_amdgcn_s_setprio(1); _Pragma("unroll") for (int m = 0; m < 4; ++m) _Pragma("unroll") for (int n = 0; n < 2; ++n) _Pragma("unroll") for (int k = 0; k < 2; ++k) \
;         acc[ai][bj][m][n] = __builtin_amdgcn_mfma_f32_16x16x32_bf16(Bt[n][k], At[m][k], acc[ai][bj][m][n], 0, 0, 0); __builtin_amdgcn_s_setprio(0); } while (0)
; #define PG8_WAIT_V(n) asm volatile("s_waitcnt vmcnt(" #n ")" ::: "memory")
; #define PG8_WAIT_L(n) asm volatile("s_waitcnt lgkmcnt(" #n ")" ::: "memory")
; #define PG8_BAR __builtin_amdgcn_s_barrier()
; #define PG8_SCHED __builtin_amdgcn_sched_barrier(0)
; template <class Epi, class Sched, bool ALIGN_EPI = false, bool SP2 = false>
; __device__ __forceinline__ void gemm_phase(PG8_LAS unsigned char* lds, const Gemm g, const Sched& S, const Epi& E) {
;     ...
;         for (int t = 0; t < nt; t += 2) {
;             const bool last = (t == nt - 2);
;             const char* a1 = cA + (size_t)(t + 1) * kstep;
;             const char* a2 = last ? nA : cA + (size_t)(t + 2) * kstep; const char* b2 = last ? nB : cB + (size_t)(t + 2) * kstep;
;             const char* a3 = a2 + kstep; const char* b3 = b2 + kstep;
;             if (last && has_next) S.a_ready(nxt);
;             if constexpr (SP2) {
;             PG8_LDB(B0, 0, 0); PG8_LDB(B1, 0, 1); PG8_SCHED; PG8_LDA(At, 0, 0); PG8_STAGE(PG8_SA(1, 1), a1 + hstep, voffA);
;             PG8_WAIT_V(8); PG8_WAIT_L(0); PG8_BAR; PG8_MMA(0, 0, At, B0); PG8_MMA(0, 1, At, B1); PG8_BAR; PG8_SCHED;
;             PG8_LDA(At, 0, 1); PG8_STAGE(PG8_SB(0, 0), b2, voffB); PG8_STAGE(PG8_SB(0, 1), b2 + hstep, voffB); PG8_STAGE(PG8_SA(0, 0), a2, voffA);
.LBB0_480:
	s_add_u32 s8, s26, 0x100
	s_addc_u32 s9, s27, 0
	s_add_i32 s54, 0, 0x10000
	s_cmp_eq_u32 s53, 40
	s_cselect_b32 s31, s23, s9
	s_cselect_b32 s30, s22, s8
	s_cselect_b32 s29, s25, s45
	s_cselect_b32 s28, s24, s44
	s_add_i32 s55, 0, 0x14000
	v_add_u32_e32 v100, s54, v234
	v_add_u32_e32 v144, s55, v234
	ds_read_b128 v[68:71], v100
	ds_read_b128 v[80:83], v100 offset:1024
	ds_read_b128 v[92:95], v100 offset:2048
	ds_read_b128 v[100:103], v100 offset:3072
	ds_read_b128 v[112:115], v144
	ds_read_b128 v[120:123], v144 offset:1024
	ds_read_b128 v[132:135], v144 offset:2048
	ds_read_b128 v[144:147], v144 offset:3072
	v_lshl_add_u64 v[198:199], s[26:27], 0, v[204:205]
	s_add_i32 m0, s40, 0xc000
	ds_read_b128 v[156:159], v236
	ds_read_b128 v[168:171], v236 offset:1024
	ds_read_b128 v[172:175], v236 offset:2048
	ds_read_b128 v[176:179], v236 offset:3072
	ds_read_b128 v[180:183], v236 offset:4096
	ds_read_b128 v[184:187], v236 offset:5120
	ds_read_b128 v[188:191], v236 offset:6144
	ds_read_b128 v[208:211], v236 offset:7168
	global_load_lds_dwordx4 v[198:199], off
	s_add_i32 m0, s40, 0xe000
	v_lshl_add_u64 v[198:199], s[26:27], 0, v[206:207]
	global_load_lds_dwordx4 v[198:199], off
	s_waitcnt vmcnt(8) lgkmcnt(0)
	s_barrier
	s_setprio 1
	v_mfma_f32_16x16x32_bf16 v[164:167], v[68:71], v[156:159], v[164:167]
	v_mfma_f32_16x16x32_bf16 v[160:163], v[92:95], v[156:159], v[160:163]
	v_mfma_f32_16x16x32_bf16 v[140:143], v[68:71], v[172:175], v[140:143]
	v_mfma_f32_16x16x32_bf16 v[136:139], v[92:95], v[172:175], v[136:139]
	v_mfma_f32_16x16x32_bf16 v[116:119], v[68:71], v[180:183], v[116:119]
	v_mfma_f32_16x16x32_bf16 v[108:111], v[92:95], v[180:183], v[108:111]
	v_mfma_f32_16x16x32_bf16 v[88:91], v[68:71], v[188:191], v[88:91]
	v_mfma_f32_16x16x32_bf16 v[84:87], v[92:95], v[188:191], v[84:87]
	v_mfma_f32_16x16x32_bf16 v[164:167], v[80:83], v[168:171], v[164:167]
	v_mfma_f32_16x16x32_bf16 v[160:163], v[100:103], v[168:171], v[160:163]
	v_mfma_f32_16x16x32_bf16 v[140:143], v[80:83], v[176:179], v[140:143]
	v_mfma_f32_16x16x32_bf16 v[136:139], v[100:103], v[176:179], v[136:139]
	v_mfma_f32_16x16x32_bf16 v[116:119], v[80:83], v[184:187], v[116:119]
	v_mfma_f32_16x16x32_bf16 v[108:111], v[100:103], v[184:187], v[108:111]
	v_mfma_f32_16x16x32_bf16 v[88:91], v[80:83], v[208:211], v[88:91]
	v_mfma_f32_16x16x32_bf16 v[84:87], v[100:103], v[208:211], v[84:87]
	v_mfma_f32_16x16x32_bf16 v[152:155], v[112:115], v[156:159], v[152:155]
	v_mfma_f32_16x16x32_bf16 v[148:151], v[132:135], v[156:159], v[148:151]
	v_mfma_f32_16x16x32_bf16 v[128:131], v[112:115], v[172:175], v[128:131]
	v_mfma_f32_16x16x32_bf16 v[124:127], v[132:135], v[172:175], v[124:127]
	v_mfma_f32_16x16x32_bf16 v[104:107], v[112:115], v[180:183], v[104:107]
	v_mfma_f32_16x16x32_bf16 v[96:99], v[132:135], v[180:183], v[96:99]
	v_mfma_f32_16x16x32_bf16 v[76:79], v[112:115], v[188:191], v[76:79]
	v_mfma_f32_16x16x32_bf16 v[72:75], v[132:135], v[188:191], v[72:75]
	v_mfma_f32_16x16x32_bf16 v[152:155], v[120:123], v[168:171], v[152:155]
	v_mfma_f32_16x16x32_bf16 v[148:151], v[144:147], v[168:171], v[148:151]
	v_mfma_f32_16x16x32_bf16 v[128:131], v[120:123], v[176:179], v[128:131]
	v_mfma_f32_16x16x32_bf16 v[124:127], v[144:147], v[176:179], v[124:127]
	v_mfma_f32_16x16x32_bf16 v[104:107], v[120:123], v[184:187], v[104:107]
	v_mfma_f32_16x16x32_bf16 v[96:99], v[144:147], v[184:187], v[96:99]
	v_mfma_f32_16x16x32_bf16 v[76:79], v[120:123], v[208:211], v[76:79]
	v_mfma_f32_16x16x32_bf16 v[72:75], v[144:147], v[208:211], v[72:75]
	s_setprio 0
	s_barrier
	s_add_i32 s26, s54, s39
	v_lshl_add_u64 v[198:199], s[28:29], 0, v[192:193]
	s_mov_b32 m0, s26
	ds_read_b128 v[156:159], v236 offset:16384
	ds_read_b128 v[168:171], v236 offset:17408
	ds_read_b128 v[172:175], v236 offset:18432
	ds_read_b128 v[176:179], v236 offset:19456
	ds_read_b128 v[180:183], v236 offset:20480
	ds_read_b128 v[184:187], v236 offset:21504
	ds_read_b128 v[188:191], v236 offset:22528
	ds_read_b128 v[208:211], v236 offset:23552
	global_load_lds_dwordx4 v[198:199], off
	s_add_i32 m0, s26, 0x2000
	s_add_u32 s26, s28, 0xb0000
	v_lshl_add_u64 v[212:213], s[28:29], 0, v[202:203]
	s_addc_u32 s27, s29, 0
	s_add_i32 s54, s55, s39
	global_load_lds_dwordx4 v[212:213], off
	v_lshl_add_u64 v[214:215], s[26:27], 0, v[192:193]
	s_mov_b32 m0, s54
	v_lshl_add_u64 v[216:217], s[30:31], 0, v[194:195]
	global_load_lds_dwordx4 v[214:215], off
	s_add_i32 m0, s54, 0x2000
	v_lshl_add_u64 v[214:215], s[26:27], 0, v[202:203]
	global_load_lds_dwordx4 v[214:215], off
	s_mov_b32 m0, s40
	v_lshl_add_u64 v[214:215], s[30:31], 0, v[0:1]
	global_load_lds_dwordx4 v[214:215], off
	s_mov_b32 m0, s41
	s_add_i32 s54, 0, 0x18000
	global_load_lds_dwordx4 v[216:217], off
	s_waitcnt vmcnt(8) lgkmcnt(0)
	s_barrier
; #define PG8_STAGE(bufoff, gbase, voff) do { _Pragma("unroll") for (int _i = 0; _i < 2; ++_i) \
;         __builtin_amdgcn_global_load_lds((const unsigned*)((const char*)(gbase) + (voff)[_i]), (PG8_LAS unsigned*)(lds + (bufoff) + ldsw + _i * 8192), 16, 0, 0); } while (0)
; #define PG8_LDA(dst, b, h) do { _Pragma("unroll") for (int m = 0; m < 4; ++m) _Pragma("unroll") for (int k = 0; k < 2; ++k) dst[m][k] = *(const PG8_LAS bf16x8*)(lds + PG8_SA(b, h) + aoff + m * 2048 + k * 1024); } while (0)
; #define PG8_LDB(dst, b, h) do { _Pragma("unroll") for (int n = 0; n < 2; ++n) _Pragma("unroll") for (int k = 0; k < 2; ++k) dst[n][k] = *(const PG8_LAS bf16x8*)(lds + PG8_SB(b, h) + boff + n * 2048 + k * 1024); } while (0)
; #define PG8_MMA(ai, bj, At, Bt) do { __builtin_amdgcn_s_setprio(1); _Pragma("unroll") for (int m = 0; m < 4; ++m) _Pragma("unroll") for (int n = 0; n < 2; ++n) _Pragma("unroll") for (int k = 0; k < 2; ++k) \
;         acc[ai][bj][m][n] = __builtin_amdgcn_mfma_f32_16x16x32_bf16(Bt[n][k], At[m][k], acc[ai][bj][m][n], 0, 0, 0); __builtin_amdgcn_s_setprio(0); } while (0)
; #define PG8_WAIT_V(n) asm volatile("s_waitcnt vmcnt(" #n ")" ::: "memory")
; #define PG8_WAIT_L(n) asm volatile("s_waitcnt lgkmcnt(" #n ")" ::: "memory")
; #define PG8_BAR __builtin_amdgcn_s_barrier()
; #define PG8_SCHED __builtin_amdgcn_sched_barrier(0)
; template <class Epi, class Sched, bool ALIGN_EPI = false, bool SP2 = false>
; __device__ __forceinline__ void gemm_phase(PG8_LAS unsigned char* lds, const Gemm g, const Sched& S, const Epi& E) {
;     ...
;             PG8_WAIT_V(8); PG8_WAIT_L(0); PG8_BAR; PG8_MMA(1, 0, At, B0); PG8_MMA(1, 1, At, B1); PG8_BAR; PG8_SCHED;
;             PG8_LDB(B0, 1, 0); PG8_LDB(B1, 1, 1); PG8_SCHED; PG8_LDA(At, 1, 0); PG8_STAGE(PG8_SA(0, 1), a2 + hstep, voffA);
;             PG8_WAIT_V(8); PG8_WAIT_L(0); PG8_BAR; PG8_MMA(0, 0, At, B0); PG8_MMA(0, 1, At, B1); PG8_BAR; PG8_SCHED;
	s_setprio 1
	v_mfma_f32_16x16x32_bf16 v[64:67], v[68:71], v[156:159], v[64:67]
	v_mfma_f32_16x16x32_bf16 v[60:63], v[92:95], v[156:159], v[60:63]
	v_mfma_f32_16x16x32_bf16 v[48:51], v[68:71], v[172:175], v[48:51]
	v_mfma_f32_16x16x32_bf16 v[44:47], v[92:95], v[172:175], v[44:47]
	v_mfma_f32_16x16x32_bf16 v[32:35], v[68:71], v[180:183], v[32:35]
	v_mfma_f32_16x16x32_bf16 v[28:31], v[92:95], v[180:183], v[28:31]
	v_mfma_f32_16x16x32_bf16 v[16:19], v[68:71], v[188:191], v[16:19]
	v_mfma_f32_16x16x32_bf16 v[12:15], v[92:95], v[188:191], v[12:15]
	v_mfma_f32_16x16x32_bf16 v[64:67], v[80:83], v[168:171], v[64:67]
	v_mfma_f32_16x16x32_bf16 v[60:63], v[100:103], v[168:171], v[60:63]
	v_mfma_f32_16x16x32_bf16 v[48:51], v[80:83], v[176:179], v[48:51]
	v_mfma_f32_16x16x32_bf16 v[44:47], v[100:103], v[176:179], v[44:47]
	v_mfma_f32_16x16x32_bf16 v[32:35], v[80:83], v[184:187], v[32:35]
	v_mfma_f32_16x16x32_bf16 v[28:31], v[100:103], v[184:187], v[28:31]
	v_mfma_f32_16x16x32_bf16 v[16:19], v[80:83], v[208:211], v[16:19]
	v_mfma_f32_16x16x32_bf16 v[12:15], v[100:103], v[208:211], v[12:15]
	v_mfma_f32_16x16x32_bf16 v[56:59], v[112:115], v[156:159], v[56:59]
	v_mfma_f32_16x16x32_bf16 v[52:55], v[132:135], v[156:159], v[52:55]
	v_mfma_f32_16x16x32_bf16 v[40:43], v[112:115], v[172:175], v[40:43]
	v_mfma_f32_16x16x32_bf16 v[36:39], v[132:135], v[172:175], v[36:39]
	v_mfma_f32_16x16x32_bf16 v[24:27], v[112:115], v[180:183], v[24:27]
	v_mfma_f32_16x16x32_bf16 v[20:23], v[132:135], v[180:183], v[20:23]
	v_mfma_f32_16x16x32_bf16 v[8:11], v[112:115], v[188:191], v[8:11]
	v_mfma_f32_16x16x32_bf16 v[4:7], v[132:135], v[188:191], v[4:7]
	v_mfma_f32_16x16x32_bf16 v[56:59], v[120:123], v[168:171], v[56:59]
	v_mfma_f32_16x16x32_bf16 v[52:55], v[144:147], v[168:171], v[52:55]
	v_mfma_f32_16x16x32_bf16 v[40:43], v[120:123], v[176:179], v[40:43]
	v_mfma_f32_16x16x32_bf16 v[36:39], v[144:147], v[176:179], v[36:39]
	v_mfma_f32_16x16x32_bf16 v[24:27], v[120:123], v[184:187], v[24:27]
	v_mfma_f32_16x16x32_bf16 v[20:23], v[144:147], v[184:187], v[20:23]
	v_mfma_f32_16x16x32_bf16 v[8:11], v[120:123], v[208:211], v[8:11]
	v_mfma_f32_16x16x32_bf16 v[4:7], v[144:147], v[208:211], v[4:7]
	s_setprio 0
	s_barrier
	s_add_i32 s55, 0, 0x1c000
	v_add_u32_e32 v100, s54, v234
	v_add_u32_e32 v144, s55, v234
	ds_read_b128 v[68:71], v100
	ds_read_b128 v[80:83], v100 offset:1024
	ds_read_b128 v[92:95], v100 offset:2048
	ds_read_b128 v[100:103], v100 offset:3072
	ds_read_b128 v[112:115], v144
	ds_read_b128 v[120:123], v144 offset:1024
	ds_read_b128 v[132:135], v144 offset:2048
	ds_read_b128 v[144:147], v144 offset:3072
	s_add_u32 s26, s30, 0xb0000
	s_addc_u32 s27, s31, 0
	s_mov_b32 m0, s42
	v_lshl_add_u64 v[218:219], s[26:27], 0, v[0:1]
	ds_read_b128 v[156:159], v236 offset:32768
	ds_read_b128 v[168:171], v236 offset:33792
	ds_read_b128 v[172:175], v236 offset:34816
	ds_read_b128 v[176:179], v236 offset:35840
	ds_read_b128 v[180:183], v236 offset:36864
	ds_read_b128 v[184:187], v236 offset:37888
	ds_read_b128 v[188:191], v236 offset:38912
	ds_read_b128 v[208:211], v236 offset:39936
	global_load_lds_dwordx4 v[218:219], off
	s_mov_b32 m0, s43
	v_lshl_add_u64 v[218:219], s[26:27], 0, v[194:195]
	global_load_lds_dwordx4 v[218:219], off
	s_waitcnt vmcnt(8) lgkmcnt(0)
	s_barrier
	s_setprio 1
	v_mfma_f32_16x16x32_bf16 v[164:167], v[68:71], v[156:159], v[164:167]
	v_mfma_f32_16x16x32_bf16 v[160:163], v[92:95], v[156:159], v[160:163]
	v_mfma_f32_16x16x32_bf16 v[140:143], v[68:71], v[172:175], v[140:143]
	v_mfma_f32_16x16x32_bf16 v[136:139], v[92:95], v[172:175], v[136:139]
	v_mfma_f32_16x16x32_bf16 v[116:119], v[68:71], v[180:183], v[116:119]
	v_mfma_f32_16x16x32_bf16 v[108:111], v[92:95], v[180:183], v[108:111]
	v_mfma_f32_16x16x32_bf16 v[88:91], v[68:71], v[188:191], v[88:91]
	v_mfma_f32_16x16x32_bf16 v[84:87], v[92:95], v[188:191], v[84:87]
	v_mfma_f32_16x16x32_bf16 v[164:167], v[80:83], v[168:171], v[164:167]
	v_mfma_f32_16x16x32_bf16 v[160:163], v[100:103], v[168:171], v[160:163]
	v_mfma_f32_16x16x32_bf16 v[140:143], v[80:83], v[176:179], v[140:143]
	v_mfma_f32_16x16x32_bf16 v[136:139], v[100:103], v[176:179], v[136:139]
	v_mfma_f32_16x16x32_bf16 v[116:119], v[80:83], v[184:187], v[116:119]
	v_mfma_f32_16x16x32_bf16 v[108:111], v[100:103], v[184:187], v[108:111]
	v_mfma_f32_16x16x32_bf16 v[88:91], v[80:83], v[208:211], v[88:91]
	v_mfma_f32_16x16x32_bf16 v[84:87], v[100:103], v[208:211], v[84:87]
	v_mfma_f32_16x16x32_bf16 v[152:155], v[112:115], v[156:159], v[152:155]
	v_mfma_f32_16x16x32_bf16 v[148:151], v[132:135], v[156:159], v[148:151]
	v_mfma_f32_16x16x32_bf16 v[128:131], v[112:115], v[172:175], v[128:131]
	v_mfma_f32_16x16x32_bf16 v[124:127], v[132:135], v[172:175], v[124:127]
	v_mfma_f32_16x16x32_bf16 v[104:107], v[112:115], v[180:183], v[104:107]
	v_mfma_f32_16x16x32_bf16 v[96:99], v[132:135], v[180:183], v[96:99]
	v_mfma_f32_16x16x32_bf16 v[76:79], v[112:115], v[188:191], v[76:79]
	v_mfma_f32_16x16x32_bf16 v[72:75], v[132:135], v[188:191], v[72:75]
	v_mfma_f32_16x16x32_bf16 v[152:155], v[120:123], v[168:171], v[152:155]
	v_mfma_f32_16x16x32_bf16 v[148:151], v[144:147], v[168:171], v[148:151]
	v_mfma_f32_16x16x32_bf16 v[128:131], v[120:123], v[176:179], v[128:131]
	v_mfma_f32_16x16x32_bf16 v[124:127], v[144:147], v[176:179], v[124:127]
	v_mfma_f32_16x16x32_bf16 v[104:107], v[120:123], v[184:187], v[104:107]
	v_mfma_f32_16x16x32_bf16 v[96:99], v[144:147], v[184:187], v[96:99]
	v_mfma_f32_16x16x32_bf16 v[76:79], v[120:123], v[208:211], v[76:79]
	v_mfma_f32_16x16x32_bf16 v[72:75], v[144:147], v[208:211], v[72:75]
	s_setprio 0
	s_barrier
; #define PG8_STAGE(bufoff, gbase, voff) do { _Pragma("unroll") for (int _i = 0; _i < 2; ++_i) \
;         __builtin_amdgcn_global_load_lds((const unsigned*)((const char*)(gbase) + (voff)[_i]), (PG8_LAS unsigned*)(lds + (bufoff) + ldsw + _i * 8192), 16, 0, 0); } while (0)
; #define PG8_LDA(dst, b, h) do { _Pragma("unroll") for (int m = 0; m < 4; ++m) _Pragma("unroll") for (int k = 0; k < 2; ++k) dst[m][k] = *(const PG8_LAS bf16x8*)(lds + PG8_SA(b, h) + aoff + m * 2048 + k * 1024); } while (0)
; #define PG8_MMA(ai, bj, At, Bt) do { __builtin_amdgcn_s_setprio(1); _Pragma("unroll") for (int m = 0; m < 4; ++m) _Pragma("unroll") for (int n = 0; n < 2; ++n) _Pragma("unroll") for (int k = 0; k < 2; ++k) \
;         acc[ai][bj][m][n] = __builtin_amdgcn_mfma_f32_16x16x32_bf16(Bt[n][k], At[m][k], acc[ai][bj][m][n], 0, 0, 0); __builtin_amdgcn_s_setprio(0); } while (0)
; #define PG8_WAIT_V(n) asm volatile("s_waitcnt vmcnt(" #n ")" ::: "memory")
; #define PG8_WAIT_L(n) asm volatile("s_waitcnt lgkmcnt(" #n ")" ::: "memory")
; #define PG8_BAR __builtin_amdgcn_s_barrier()
; #define PG8_SCHED __builtin_amdgcn_sched_barrier(0)
; template <class Epi, class Sched, bool ALIGN_EPI = false, bool SP2 = false>
; __device__ __forceinline__ void gemm_phase(PG8_LAS unsigned char* lds, const Gemm g, const Sched& S, const Epi& E) {
;     ...
;         for (int t = 0; t < nt; t += 2) {
;             const bool last = (t == nt - 2);
;             const char* a1 = cA + (size_t)(t + 1) * kstep;
;             const char* a2 = last ? nA : cA + (size_t)(t + 2) * kstep; const char* b2 = last ? nB : cB + (size_t)(t + 2) * kstep;
;     ...
;             PG8_LDA(At, 1, 1); PG8_STAGE(PG8_SB(1, 0), b3, voffB); PG8_STAGE(PG8_SB(1, 1), b3 + hstep, voffB); PG8_STAGE(PG8_SA(1, 0), a3, voffA);
;             PG8_WAIT_V(8); PG8_WAIT_L(0); PG8_BAR; PG8_MMA(1, 0, At, B0); PG8_MMA(1, 1, At, B1); PG8_BAR; PG8_SCHED;
	s_add_i32 s26, s54, s39
	v_lshl_add_u64 v[198:199], v[198:199], 0, s[82:83]
	s_mov_b32 m0, s26
	ds_read_b128 v[156:159], v236 offset:49152
	ds_read_b128 v[168:171], v236 offset:50176
	ds_read_b128 v[172:175], v236 offset:51200
	ds_read_b128 v[176:179], v236 offset:52224
	ds_read_b128 v[180:183], v236 offset:53248
	ds_read_b128 v[184:187], v236 offset:54272
	ds_read_b128 v[188:191], v236 offset:55296
	ds_read_b128 v[208:211], v236 offset:56320
	global_load_lds_dwordx4 v[198:199], off
	s_add_i32 m0, s26, 0x2000
	s_add_u32 s26, s28, 0xb0080
	v_lshl_add_u64 v[198:199], v[212:213], 0, s[82:83]
	s_addc_u32 s27, s29, 0
	s_add_i32 s28, s55, s39
	global_load_lds_dwordx4 v[198:199], off
	s_mov_b32 m0, s28
	v_lshl_add_u64 v[198:199], s[26:27], 0, v[192:193]
	global_load_lds_dwordx4 v[198:199], off
	s_add_i32 m0, s28, 0x2000
	v_lshl_add_u64 v[198:199], s[26:27], 0, v[202:203]
	global_load_lds_dwordx4 v[198:199], off
	s_mov_b32 m0, s47
	v_lshl_add_u64 v[198:199], v[214:215], 0, s[82:83]
	global_load_lds_dwordx4 v[198:199], off
	s_mov_b32 m0, s48
	v_lshl_add_u64 v[198:199], v[216:217], 0, s[82:83]
	global_load_lds_dwordx4 v[198:199], off
	s_waitcnt vmcnt(8) lgkmcnt(0)
	s_barrier
	s_setprio 1
	v_mfma_f32_16x16x32_bf16 v[64:67], v[68:71], v[156:159], v[64:67]
	v_mfma_f32_16x16x32_bf16 v[60:63], v[92:95], v[156:159], v[60:63]
	v_mfma_f32_16x16x32_bf16 v[48:51], v[68:71], v[172:175], v[48:51]
	v_mfma_f32_16x16x32_bf16 v[44:47], v[92:95], v[172:175], v[44:47]
	v_mfma_f32_16x16x32_bf16 v[32:35], v[68:71], v[180:183], v[32:35]
	v_mfma_f32_16x16x32_bf16 v[28:31], v[92:95], v[180:183], v[28:31]
	v_mfma_f32_16x16x32_bf16 v[16:19], v[68:71], v[188:191], v[16:19]
	v_mfma_f32_16x16x32_bf16 v[12:15], v[92:95], v[188:191], v[12:15]
	v_mfma_f32_16x16x32_bf16 v[64:67], v[80:83], v[168:171], v[64:67]
	v_mfma_f32_16x16x32_bf16 v[60:63], v[100:103], v[168:171], v[60:63]
	v_mfma_f32_16x16x32_bf16 v[48:51], v[80:83], v[176:179], v[48:51]
	v_mfma_f32_16x16x32_bf16 v[44:47], v[100:103], v[176:179], v[44:47]
	v_mfma_f32_16x16x32_bf16 v[32:35], v[80:83], v[184:187], v[32:35]
	v_mfma_f32_16x16x32_bf16 v[28:31], v[100:103], v[184:187], v[28:31]
	v_mfma_f32_16x16x32_bf16 v[16:19], v[80:83], v[208:211], v[16:19]
	v_mfma_f32_16x16x32_bf16 v[12:15], v[100:103], v[208:211], v[12:15]
	v_mfma_f32_16x16x32_bf16 v[56:59], v[112:115], v[156:159], v[56:59]
	v_mfma_f32_16x16x32_bf16 v[52:55], v[132:135], v[156:159], v[52:55]
	v_mfma_f32_16x16x32_bf16 v[40:43], v[112:115], v[172:175], v[40:43]
	v_mfma_f32_16x16x32_bf16 v[36:39], v[132:135], v[172:175], v[36:39]
	v_mfma_f32_16x16x32_bf16 v[24:27], v[112:115], v[180:183], v[24:27]
	v_mfma_f32_16x16x32_bf16 v[20:23], v[132:135], v[180:183], v[20:23]
	v_mfma_f32_16x16x32_bf16 v[8:11], v[112:115], v[188:191], v[8:11]
	v_mfma_f32_16x16x32_bf16 v[4:7], v[132:135], v[188:191], v[4:7]
	v_mfma_f32_16x16x32_bf16 v[56:59], v[120:123], v[168:171], v[56:59]
	v_mfma_f32_16x16x32_bf16 v[52:55], v[144:147], v[168:171], v[52:55]
	v_mfma_f32_16x16x32_bf16 v[40:43], v[120:123], v[176:179], v[40:43]
	v_mfma_f32_16x16x32_bf16 v[36:39], v[144:147], v[176:179], v[36:39]
	v_mfma_f32_16x16x32_bf16 v[24:27], v[120:123], v[184:187], v[24:27]
	v_mfma_f32_16x16x32_bf16 v[20:23], v[144:147], v[184:187], v[20:23]
	v_mfma_f32_16x16x32_bf16 v[8:11], v[120:123], v[208:211], v[8:11]
	v_mfma_f32_16x16x32_bf16 v[4:7], v[144:147], v[208:211], v[4:7]
	s_setprio 0
	s_barrier
	s_add_i32 s53, s53, 2
	s_add_u32 s44, s44, 0x100
	s_addc_u32 s45, s45, 0
	s_cmp_gt_u32 s53, 41
	s_mov_b64 s[26:27], s[8:9]
	s_cbranch_scc0 .LBB0_480
	s_and_b64 vcc, exec, s[20:21]
	s_cbranch_vccz .LBB0_483
	s_barrier
